# GEMM K-loops: M0 wait state filled by the address add instead of s_nop; constant LDS offsets folded into ds_read offsets; accumulator zeroing once
# speedup vs baseline: 1.0057x; 1.0057x over previous
; #define PG8_STAGE(bufoff, gbase, voff) do { _Pragma("unroll") for (int _i = 0; _i < 2; ++_i) \
;         __builtin_amdgcn_global_load_lds((const unsigned*)((const char*)(gbase) + (voff)[_i]), (PG8_LAS unsigned*)(lds + (bufoff) + ldsw + _i * 8192), 16, 0, 0); } while (0)
; #define PG8_WAIT_V(n) asm volatile("s_waitcnt vmcnt(" #n ")" ::: "memory")
; #define PG8_BAR __builtin_amdgcn_s_barrier()
; template <class Epi, class Sched, bool ALIGN_EPI = false, bool SP2 = false>
; __device__ __forceinline__ void gemm_phase(PG8_LAS unsigned char* lds, const Gemm g, const Sched& S, const Epi& E) {
;     ...
;     const int aoff = lds_byte(wr * 64 + fr, fq * 8), boff = lds_byte(wc * 32 + fr, fq * 8);
;     ...
;         PG8_STAGE(PG8_SB(0, 0), cB, voffB); PG8_STAGE(PG8_SB(0, 1), cB + hstep, voffB); PG8_STAGE(PG8_SA(0, 0), cA, voffA); PG8_STAGE(PG8_SA(0, 1), cA + hstep, voffA);
;         if (wr == 1) PG8_BAR;
;         PG8_WAIT_V(2); PG8_BAR;
;         PG8_STAGE(PG8_SB(1, 0), cB + kstep, voffB); PG8_STAGE(PG8_SA(1, 0), cA + kstep, voffA); PG8_STAGE(PG8_SB(1, 1), cB + hstep + kstep, voffB);
;         PG8_WAIT_V(6); PG8_BAR;
.LBB0_330:
	s_add_u32 s50, s90, 0x15800000
	s_addc_u32 s51, s91, 0
	s_add_i32 m0, s63, 0x18000
	v_lshl_add_u64 v[2:3], v[2:3], 0, s[24:25]
	s_waitcnt vmcnt(2)
	s_barrier
	global_load_lds_dwordx4 v[2:3], off
	v_lshl_add_u64 v[2:3], v[4:5], 0, s[24:25]
	s_add_i32 m0, s63, 0x1a000
	s_add_i32 s68, s63, 0x8000
	global_load_lds_dwordx4 v[2:3], off
	v_lshl_add_u64 v[2:3], v[10:11], 0, s[24:25]
	s_mov_b32 m0, s68
	s_add_i32 s69, s63, 0xa000
	global_load_lds_dwordx4 v[2:3], off
	v_lshl_add_u64 v[2:3], v[12:13], 0, s[24:25]
	s_mov_b32 m0, s69
	v_lshrrev_b32_e32 v21, 1, v19
	global_load_lds_dwordx4 v[2:3], off
	s_add_i32 m0, s63, 0x1c000
	v_lshl_add_u64 v[2:3], v[6:7], 0, s[24:25]
	global_load_lds_dwordx4 v[2:3], off
	v_lshl_add_u64 v[2:3], v[8:9], 0, s[24:25]
	s_add_i32 m0, s63, 0x1e000
	s_lshr_b32 s7, s7, 26
	global_load_lds_dwordx4 v[2:3], off
	v_and_b32_e32 v21, 24, v21
	v_and_b32_e32 v20, 15, v19
	s_add_i32 s7, s6, s7
	v_lshlrev_b32_e32 v22, 1, v21
	v_lshlrev_b32_e32 v19, 2, v19
	s_ashr_i32 s67, s7, 6
	v_lshl_or_b32 v166, s42, 6, v20
	v_lshl_or_b32 v20, v20, 6, v22
	s_lshl_b32 s7, s42, 13
	v_and_b32_e32 v19, 32, v19
	v_bitop3_b32 v22, v20, s7, v19 bitop3:0xde
	s_lshl_b32 s7, s39, 5
	s_and_b32 s7, s7, 0x60
	s_lshl_b32 s39, s7, 7
	s_cmp_gt_i32 s6, 63
	s_cselect_b64 s[52:53], -1, 0
	s_add_i32 s70, s67, -2
	s_cmpk_lt_u32 s9, 0x100
	s_cselect_b64 s[54:55], -1, 0
	s_lshl_b32 s72, s33, 3
	s_abs_i32 s74, s72
	v_cvt_f32_u32_e32 v2, s74
	v_add_u32_e32 v0, v15, v0
	v_or_b32_e32 v168, s7, v21
	s_sub_i32 s6, 0, s74
	v_rcp_iflag_f32_e32 v2, v2
	v_add_lshl_u32 v0, v0, v14, 1
	s_waitcnt vmcnt(6)
	v_lshl_add_u64 v[154:155], s[10:11], 0, v[0:1]
	v_mul_f32_e32 v2, 0x4f7ffffe, v2
	v_cvt_u32_f32_e32 v2, v2
	v_add_u32_e32 v0, v18, v16
	v_add_lshl_u32 v0, v0, v17, 1
	v_bitop3_b32 v167, v20, s39, v19 bitop3:0xde
	v_add_u32_e32 v167, 0x10000, v167
	v_readfirstlane_b32 s7, v2
	s_mul_i32 s6, s6, s7
	s_mul_hi_u32 s6, s7, s6
	s_ashr_i32 s9, s8, 31
	s_lshl_b32 s71, s33, 4
	s_bfe_i32 s73, s33, 0x1001c
	s_mov_b32 s75, 0
	s_waitcnt lgkmcnt(0)
	s_add_i32 s95, s7, s6
	s_waitcnt vmcnt(0)
	v_lshl_add_u64 v[156:157], s[10:11], 0, v[0:1]
	v_add_u32_e32 v169, 0, v22
	s_movk_i32 s39, 0x5000
	s_barrier
	s_branch .LBB0_333

; #define PG8_STAGE(bufoff, gbase, voff) do { _Pragma("unroll") for (int _i = 0; _i < 2; ++_i) \
;         __builtin_amdgcn_global_load_lds((const unsigned*)((const char*)(gbase) + (voff)[_i]), (PG8_LAS unsigned*)(lds + (bufoff) + ldsw + _i * 8192), 16, 0, 0); } while (0)
; #define PG8_LDA(dst, b, h) do { _Pragma("unroll") for (int m = 0; m < 4; ++m) _Pragma("unroll") for (int k = 0; k < 2; ++k) dst[m][k] = *(const PG8_LAS bf16x8*)(lds + PG8_SA(b, h) + aoff + m * 2048 + k * 1024); } while (0)
; #define PG8_LDB(dst, b, h) do { _Pragma("unroll") for (int n = 0; n < 2; ++n) _Pragma("unroll") for (int k = 0; k < 2; ++k) dst[n][k] = *(const PG8_LAS bf16x8*)(lds + PG8_SB(b, h) + boff + n * 2048 + k * 1024); } while (0)
; #define PG8_WAIT_V(n) asm volatile("s_waitcnt vmcnt(" #n ")" ::: "memory")
; #define PG8_WAIT_L(n) asm volatile("s_waitcnt lgkmcnt(" #n ")" ::: "memory")
; #define PG8_BAR __builtin_amdgcn_s_barrier()
; #define PG8_SCHED __builtin_amdgcn_sched_barrier(0)
; template <class Epi, class Sched, bool ALIGN_EPI = false, bool SP2 = false>
; __device__ __forceinline__ void gemm_phase(PG8_LAS unsigned char* lds, const Gemm g, const Sched& S, const Epi& E) {
;     ...
;         const bool has_next = S.next(ui + 1, nxt);
;         const char* nA = has_next ? (const char*)g.A + (size_t)nxt.pm * tstep : cA; const char* nB = has_next ? (const char*)g.Bt + (size_t)nxt.pn * tstep : cB;
;         for (int t = 0; t < nt; t += 2) {
;             const bool last = (t == nt - 2);
;             const char* a1 = cA + (size_t)(t + 1) * kstep;
;             const char* a2 = last ? nA : cA + (size_t)(t + 2) * kstep; const char* b2 = last ? nB : cB + (size_t)(t + 2) * kstep;
;             const char* a3 = a2 + kstep; const char* b3 = b2 + kstep;
;             if (last && has_next) S.a_ready(nxt);
;             if constexpr (SP2) {
;             PG8_LDB(B0, 0, 0); PG8_LDB(B1, 0, 1); PG8_SCHED; PG8_LDA(At, 0, 0); PG8_STAGE(PG8_SA(1, 1), a1 + hstep, voffA);
;             PG8_WAIT_V(8); PG8_WAIT_L(0); PG8_BAR; PG8_MMA(0, 0, At, B0); PG8_MMA(0, 1, At, B1); PG8_BAR; PG8_SCHED;
;             PG8_LDA(At, 0, 1); PG8_STAGE(PG8_SB(0, 0), b2, voffB); PG8_STAGE(PG8_SB(0, 1), b2 + hstep, voffB); PG8_STAGE(PG8_SA(0, 0), a2, voffA);
;             PG8_WAIT_V(8); PG8_WAIT_L(0); PG8_BAR; PG8_MMA(1, 0, At, B0); PG8_MMA(1, 1, At, B1); PG8_BAR; PG8_SCHED;
.LBB0_341:
	s_add_i32 s44, s20, 2
	s_add_u32 s45, s16, 0x80
	s_addc_u32 s21, s17, 0
	s_add_i32 s58, 0, 0x10000
	s_cmp_eq_u32 s70, s20
	s_cselect_b32 s21, s7, s21
	s_cselect_b32 s20, s6, s45
	s_cselect_b32 s47, s57, s39
	s_cselect_b32 s46, s56, s33
	s_add_i32 s45, 0, 0x14000
	ds_read_b128 v[82:85], v167
	ds_read_b128 v[86:89], v167 offset:1024
	ds_read_b128 v[138:141], v167 offset:2048
	ds_read_b128 v[142:145], v167 offset:3072
	ds_read_b128 v[158:161], v167 offset:16384
	ds_read_b128 v[162:165], v167 offset:17408
	ds_read_b128 v[170:173], v167 offset:18432
	ds_read_b128 v[174:177], v167 offset:19456
	v_lshl_add_u64 v[210:211], s[16:17], 0, v[154:155]
	s_add_i32 m0, s63, 0xc000
	ds_read_b128 v[178:181], v169
	ds_read_b128 v[182:185], v169 offset:1024
	ds_read_b128 v[186:189], v169 offset:2048
	ds_read_b128 v[190:193], v169 offset:3072
	ds_read_b128 v[194:197], v169 offset:4096
	ds_read_b128 v[198:201], v169 offset:5120
	ds_read_b128 v[202:205], v169 offset:6144
	ds_read_b128 v[206:209], v169 offset:7168
	global_load_lds_dwordx4 v[210:211], off
	s_add_i32 m0, s63, 0xe000
	v_lshl_add_u64 v[210:211], s[16:17], 0, v[156:157]
	global_load_lds_dwordx4 v[210:211], off
	s_waitcnt vmcnt(8)
	s_waitcnt lgkmcnt(0)
	s_barrier
	s_setprio 1
	s_waitcnt lgkmcnt(0)
	v_mfma_f32_16x16x32_bf16 v[134:137], v[82:85], v[178:181], v[134:137]
	v_mfma_f32_16x16x32_bf16 v[130:133], v[138:141], v[178:181], v[130:133]
	v_mfma_f32_16x16x32_bf16 v[126:129], v[82:85], v[186:189], v[126:129]
	v_mfma_f32_16x16x32_bf16 v[122:125], v[138:141], v[186:189], v[122:125]
	v_mfma_f32_16x16x32_bf16 v[118:121], v[82:85], v[194:197], v[118:121]
	v_mfma_f32_16x16x32_bf16 v[114:117], v[138:141], v[194:197], v[114:117]
	v_mfma_f32_16x16x32_bf16 v[110:113], v[82:85], v[202:205], v[110:113]
	v_mfma_f32_16x16x32_bf16 v[106:109], v[138:141], v[202:205], v[106:109]
	v_mfma_f32_16x16x32_bf16 v[134:137], v[86:89], v[182:185], v[134:137]
	v_mfma_f32_16x16x32_bf16 v[130:133], v[142:145], v[182:185], v[130:133]
	v_mfma_f32_16x16x32_bf16 v[126:129], v[86:89], v[190:193], v[126:129]
	v_mfma_f32_16x16x32_bf16 v[122:125], v[142:145], v[190:193], v[122:125]
	v_mfma_f32_16x16x32_bf16 v[118:121], v[86:89], v[198:201], v[118:121]
	v_mfma_f32_16x16x32_bf16 v[114:117], v[142:145], v[198:201], v[114:117]
	v_mfma_f32_16x16x32_bf16 v[110:113], v[86:89], v[206:209], v[110:113]
	v_mfma_f32_16x16x32_bf16 v[106:109], v[142:145], v[206:209], v[106:109]
	s_setprio 0
	s_setprio 1
	v_mfma_f32_16x16x32_bf16 v[62:65], v[158:161], v[178:181], v[62:65]
	v_mfma_f32_16x16x32_bf16 v[58:61], v[170:173], v[178:181], v[58:61]
	v_mfma_f32_16x16x32_bf16 v[54:57], v[158:161], v[186:189], v[54:57]
	v_mfma_f32_16x16x32_bf16 v[50:53], v[170:173], v[186:189], v[50:53]
	v_mfma_f32_16x16x32_bf16 v[46:49], v[158:161], v[194:197], v[46:49]
	v_mfma_f32_16x16x32_bf16 v[42:45], v[170:173], v[194:197], v[42:45]
	v_mfma_f32_16x16x32_bf16 v[38:41], v[158:161], v[202:205], v[38:41]
	v_mfma_f32_16x16x32_bf16 v[34:37], v[170:173], v[202:205], v[34:37]
	v_mfma_f32_16x16x32_bf16 v[62:65], v[162:165], v[182:185], v[62:65]
	v_mfma_f32_16x16x32_bf16 v[58:61], v[174:177], v[182:185], v[58:61]
	v_mfma_f32_16x16x32_bf16 v[54:57], v[162:165], v[190:193], v[54:57]
	v_mfma_f32_16x16x32_bf16 v[50:53], v[174:177], v[190:193], v[50:53]
	v_mfma_f32_16x16x32_bf16 v[46:49], v[162:165], v[198:201], v[46:49]
	v_mfma_f32_16x16x32_bf16 v[42:45], v[174:177], v[198:201], v[42:45]
	v_mfma_f32_16x16x32_bf16 v[38:41], v[162:165], v[206:209], v[38:41]
	v_mfma_f32_16x16x32_bf16 v[34:37], v[174:177], v[206:209], v[34:37]
	s_setprio 0
	s_barrier
	s_add_i32 s58, s58, s62
	v_lshl_add_u64 v[210:211], s[46:47], 0, v[148:149]
	s_mov_b32 m0, s58
	ds_read_b128 v[178:181], v169 offset:16384
	ds_read_b128 v[182:185], v169 offset:17408
	ds_read_b128 v[186:189], v169 offset:18432
	ds_read_b128 v[190:193], v169 offset:19456
	ds_read_b128 v[194:197], v169 offset:20480
	ds_read_b128 v[198:201], v169 offset:21504
	ds_read_b128 v[202:205], v169 offset:22528
	ds_read_b128 v[206:209], v169 offset:23552
	global_load_lds_dwordx4 v[210:211], off
	s_add_i32 m0, s58, 0x2000
	v_lshl_add_u64 v[212:213], s[46:47], 0, v[152:153]
	s_add_u32 s46, s46, s10
	s_addc_u32 s47, s47, s11
	s_add_i32 s45, s45, s62
	global_load_lds_dwordx4 v[212:213], off
	v_lshl_add_u64 v[214:215], s[46:47], 0, v[148:149]
	s_mov_b32 m0, s45
	v_lshl_add_u64 v[218:219], s[46:47], 0, v[152:153]
	global_load_lds_dwordx4 v[214:215], off
	s_add_i32 m0, s45, 0x2000
	v_lshl_add_u64 v[220:221], s[20:21], 0, v[146:147]
	global_load_lds_dwordx4 v[218:219], off
	s_mov_b32 m0, s63
	v_lshl_add_u64 v[222:223], s[20:21], 0, v[150:151]
	global_load_lds_dwordx4 v[220:221], off
	s_mov_b32 m0, s64
	s_nop 0
	global_load_lds_dwordx4 v[222:223], off
	s_waitcnt vmcnt(8)
	s_waitcnt lgkmcnt(0)
	s_barrier
; #define PG8_STAGE(bufoff, gbase, voff) do { _Pragma("unroll") for (int _i = 0; _i < 2; ++_i) \
;         __builtin_amdgcn_global_load_lds((const unsigned*)((const char*)(gbase) + (voff)[_i]), (PG8_LAS unsigned*)(lds + (bufoff) + ldsw + _i * 8192), 16, 0, 0); } while (0)
; #define PG8_LDA(dst, b, h) do { _Pragma("unroll") for (int m = 0; m < 4; ++m) _Pragma("unroll") for (int k = 0; k < 2; ++k) dst[m][k] = *(const PG8_LAS bf16x8*)(lds + PG8_SA(b, h) + aoff + m * 2048 + k * 1024); } while (0)
; #define PG8_LDB(dst, b, h) do { _Pragma("unroll") for (int n = 0; n < 2; ++n) _Pragma("unroll") for (int k = 0; k < 2; ++k) dst[n][k] = *(const PG8_LAS bf16x8*)(lds + PG8_SB(b, h) + boff + n * 2048 + k * 1024); } while (0)
; #define PG8_MMA(ai, bj, At, Bt) do { __builtin_amdgcn_s_setprio(1); _Pragma("unroll") for (int m = 0; m < 4; ++m) _Pragma("unroll") for (int n = 0; n < 2; ++n) _Pragma("unroll") for (int k = 0; k < 2; ++k) \
;         acc[ai][bj][m][n] = __builtin_amdgcn_mfma_f32_16x16x32_bf16(Bt[n][k], At[m][k], acc[ai][bj][m][n], 0, 0, 0); __builtin_amdgcn_s_setprio(0); } while (0)
; #define PG8_WAIT_V(n) asm volatile("s_waitcnt vmcnt(" #n ")" ::: "memory")
; #define PG8_WAIT_L(n) asm volatile("s_waitcnt lgkmcnt(" #n ")" ::: "memory")
; #define PG8_BAR __builtin_amdgcn_s_barrier()
; #define PG8_SCHED __builtin_amdgcn_sched_barrier(0)
; template <class Epi, class Sched, bool ALIGN_EPI = false, bool SP2 = false>
; __device__ __forceinline__ void gemm_phase(PG8_LAS unsigned char* lds, const Gemm g, const Sched& S, const Epi& E) {
;     ...
;             PG8_WAIT_V(8); PG8_WAIT_L(0); PG8_BAR; PG8_MMA(1, 0, At, B0); PG8_MMA(1, 1, At, B1); PG8_BAR; PG8_SCHED;
;             PG8_LDB(B0, 1, 0); PG8_LDB(B1, 1, 1); PG8_SCHED; PG8_LDA(At, 1, 0); PG8_STAGE(PG8_SA(0, 1), a2 + hstep, voffA);
;             PG8_WAIT_V(8); PG8_WAIT_L(0); PG8_BAR; PG8_MMA(0, 0, At, B0); PG8_MMA(0, 1, At, B1); PG8_BAR; PG8_SCHED;
	s_setprio 1
	s_waitcnt lgkmcnt(0)
	v_mfma_f32_16x16x32_bf16 v[102:105], v[82:85], v[178:181], v[102:105]
	v_mfma_f32_16x16x32_bf16 v[98:101], v[138:141], v[178:181], v[98:101]
	v_mfma_f32_16x16x32_bf16 v[94:97], v[82:85], v[186:189], v[94:97]
	v_mfma_f32_16x16x32_bf16 v[90:93], v[138:141], v[186:189], v[90:93]
	v_mfma_f32_16x16x32_bf16 v[78:81], v[82:85], v[194:197], v[78:81]
	v_mfma_f32_16x16x32_bf16 v[74:77], v[138:141], v[194:197], v[74:77]
	v_mfma_f32_16x16x32_bf16 v[70:73], v[82:85], v[202:205], v[70:73]
	v_mfma_f32_16x16x32_bf16 v[66:69], v[138:141], v[202:205], v[66:69]
	v_mfma_f32_16x16x32_bf16 v[102:105], v[86:89], v[182:185], v[102:105]
	v_mfma_f32_16x16x32_bf16 v[98:101], v[142:145], v[182:185], v[98:101]
	v_mfma_f32_16x16x32_bf16 v[94:97], v[86:89], v[190:193], v[94:97]
	v_mfma_f32_16x16x32_bf16 v[90:93], v[142:145], v[190:193], v[90:93]
	v_mfma_f32_16x16x32_bf16 v[78:81], v[86:89], v[198:201], v[78:81]
	v_mfma_f32_16x16x32_bf16 v[74:77], v[142:145], v[198:201], v[74:77]
	v_mfma_f32_16x16x32_bf16 v[70:73], v[86:89], v[206:209], v[70:73]
	v_mfma_f32_16x16x32_bf16 v[66:69], v[142:145], v[206:209], v[66:69]
	s_setprio 0
	s_setprio 1
	v_mfma_f32_16x16x32_bf16 v[30:33], v[158:161], v[178:181], v[30:33]
	v_mfma_f32_16x16x32_bf16 v[26:29], v[170:173], v[178:181], v[26:29]
	v_mfma_f32_16x16x32_bf16 v[22:25], v[158:161], v[186:189], v[22:25]
	v_mfma_f32_16x16x32_bf16 v[18:21], v[170:173], v[186:189], v[18:21]
	v_mfma_f32_16x16x32_bf16 v[14:17], v[158:161], v[194:197], v[14:17]
	v_mfma_f32_16x16x32_bf16 v[10:13], v[170:173], v[194:197], v[10:13]
	v_mfma_f32_16x16x32_bf16 v[6:9], v[158:161], v[202:205], v[6:9]
	v_mfma_f32_16x16x32_bf16 v[2:5], v[170:173], v[202:205], v[2:5]
	v_mfma_f32_16x16x32_bf16 v[30:33], v[162:165], v[182:185], v[30:33]
	v_mfma_f32_16x16x32_bf16 v[26:29], v[174:177], v[182:185], v[26:29]
	v_mfma_f32_16x16x32_bf16 v[22:25], v[162:165], v[190:193], v[22:25]
	v_mfma_f32_16x16x32_bf16 v[18:21], v[174:177], v[190:193], v[18:21]
	v_mfma_f32_16x16x32_bf16 v[14:17], v[162:165], v[198:201], v[14:17]
	v_mfma_f32_16x16x32_bf16 v[10:13], v[174:177], v[198:201], v[10:13]
	v_mfma_f32_16x16x32_bf16 v[6:9], v[162:165], v[206:209], v[6:9]
	v_mfma_f32_16x16x32_bf16 v[2:5], v[174:177], v[206:209], v[2:5]
	s_setprio 0
	s_barrier
	s_add_i32 s45, 0, 0x18000
	s_add_i32 s46, 0, 0x1c000
	ds_read_b128 v[82:85], v167 offset:32768
	ds_read_b128 v[86:89], v167 offset:33792
	ds_read_b128 v[138:141], v167 offset:34816
	ds_read_b128 v[142:145], v167 offset:35840
	ds_read_b128 v[158:161], v167 offset:49152
	ds_read_b128 v[162:165], v167 offset:50176
	ds_read_b128 v[170:173], v167 offset:51200
	ds_read_b128 v[174:177], v167 offset:52224
	s_add_u32 s20, s20, s10
	s_addc_u32 s21, s21, s11
	s_mov_b32 m0, s65
	v_lshl_add_u64 v[224:225], s[20:21], 0, v[146:147]
	ds_read_b128 v[178:181], v169 offset:32768
	ds_read_b128 v[182:185], v169 offset:33792
	ds_read_b128 v[186:189], v169 offset:34816
	ds_read_b128 v[190:193], v169 offset:35840
	ds_read_b128 v[194:197], v169 offset:36864
	ds_read_b128 v[198:201], v169 offset:37888
	ds_read_b128 v[202:205], v169 offset:38912
	ds_read_b128 v[206:209], v169 offset:39936
	global_load_lds_dwordx4 v[224:225], off
	s_mov_b32 m0, s66
	v_lshl_add_u64 v[224:225], s[20:21], 0, v[150:151]
	global_load_lds_dwordx4 v[224:225], off
	s_waitcnt vmcnt(8)
	s_waitcnt lgkmcnt(0)
	s_barrier
	s_setprio 1
	s_waitcnt lgkmcnt(0)
	v_mfma_f32_16x16x32_bf16 v[134:137], v[82:85], v[178:181], v[134:137]
	v_mfma_f32_16x16x32_bf16 v[130:133], v[138:141], v[178:181], v[130:133]
	v_mfma_f32_16x16x32_bf16 v[126:129], v[82:85], v[186:189], v[126:129]
	v_mfma_f32_16x16x32_bf16 v[122:125], v[138:141], v[186:189], v[122:125]
	v_mfma_f32_16x16x32_bf16 v[118:121], v[82:85], v[194:197], v[118:121]
	v_mfma_f32_16x16x32_bf16 v[114:117], v[138:141], v[194:197], v[114:117]
	v_mfma_f32_16x16x32_bf16 v[110:113], v[82:85], v[202:205], v[110:113]
	v_mfma_f32_16x16x32_bf16 v[106:109], v[138:141], v[202:205], v[106:109]
	v_mfma_f32_16x16x32_bf16 v[134:137], v[86:89], v[182:185], v[134:137]
	v_mfma_f32_16x16x32_bf16 v[130:133], v[142:145], v[182:185], v[130:133]
	v_mfma_f32_16x16x32_bf16 v[126:129], v[86:89], v[190:193], v[126:129]
	v_mfma_f32_16x16x32_bf16 v[122:125], v[142:145], v[190:193], v[122:125]
	v_mfma_f32_16x16x32_bf16 v[118:121], v[86:89], v[198:201], v[118:121]
	v_mfma_f32_16x16x32_bf16 v[114:117], v[142:145], v[198:201], v[114:117]
	v_mfma_f32_16x16x32_bf16 v[110:113], v[86:89], v[206:209], v[110:113]
	v_mfma_f32_16x16x32_bf16 v[106:109], v[142:145], v[206:209], v[106:109]
	s_setprio 0
	s_setprio 1
	v_mfma_f32_16x16x32_bf16 v[62:65], v[158:161], v[178:181], v[62:65]
	v_mfma_f32_16x16x32_bf16 v[58:61], v[170:173], v[178:181], v[58:61]
	v_mfma_f32_16x16x32_bf16 v[54:57], v[158:161], v[186:189], v[54:57]
	v_mfma_f32_16x16x32_bf16 v[50:53], v[170:173], v[186:189], v[50:53]
	v_mfma_f32_16x16x32_bf16 v[46:49], v[158:161], v[194:197], v[46:49]
	v_mfma_f32_16x16x32_bf16 v[42:45], v[170:173], v[194:197], v[42:45]
	v_mfma_f32_16x16x32_bf16 v[38:41], v[158:161], v[202:205], v[38:41]
	v_mfma_f32_16x16x32_bf16 v[34:37], v[170:173], v[202:205], v[34:37]
	v_mfma_f32_16x16x32_bf16 v[62:65], v[162:165], v[182:185], v[62:65]
	v_mfma_f32_16x16x32_bf16 v[58:61], v[174:177], v[182:185], v[58:61]
	v_mfma_f32_16x16x32_bf16 v[54:57], v[162:165], v[190:193], v[54:57]
	v_mfma_f32_16x16x32_bf16 v[50:53], v[174:177], v[190:193], v[50:53]
	v_mfma_f32_16x16x32_bf16 v[46:49], v[162:165], v[198:201], v[46:49]
	v_mfma_f32_16x16x32_bf16 v[42:45], v[174:177], v[198:201], v[42:45]
	v_mfma_f32_16x16x32_bf16 v[38:41], v[162:165], v[206:209], v[38:41]
	v_mfma_f32_16x16x32_bf16 v[34:37], v[174:177], v[206:209], v[34:37]
	s_setprio 0
	s_barrier
; #define PG8_STAGE(bufoff, gbase, voff) do { _Pragma("unroll") for (int _i = 0; _i < 2; ++_i) \
;         __builtin_amdgcn_global_load_lds((const unsigned*)((const char*)(gbase) + (voff)[_i]), (PG8_LAS unsigned*)(lds + (bufoff) + ldsw + _i * 8192), 16, 0, 0); } while (0)
; #define PG8_LDA(dst, b, h) do { _Pragma("unroll") for (int m = 0; m < 4; ++m) _Pragma("unroll") for (int k = 0; k < 2; ++k) dst[m][k] = *(const PG8_LAS bf16x8*)(lds + PG8_SA(b, h) + aoff + m * 2048 + k * 1024); } while (0)
; #define PG8_MMA(ai, bj, At, Bt) do { __builtin_amdgcn_s_setprio(1); _Pragma("unroll") for (int m = 0; m < 4; ++m) _Pragma("unroll") for (int n = 0; n < 2; ++n) _Pragma("unroll") for (int k = 0; k < 2; ++k) \
;         acc[ai][bj][m][n] = __builtin_amdgcn_mfma_f32_16x16x32_bf16(Bt[n][k], At[m][k], acc[ai][bj][m][n], 0, 0, 0); __builtin_amdgcn_s_setprio(0); } while (0)
; #define PG8_WAIT_V(n) asm volatile("s_waitcnt vmcnt(" #n ")" ::: "memory")
; #define PG8_WAIT_L(n) asm volatile("s_waitcnt lgkmcnt(" #n ")" ::: "memory")
; #define PG8_BAR __builtin_amdgcn_s_barrier()
; #define PG8_SCHED __builtin_amdgcn_sched_barrier(0)
; template <class Epi, class Sched, bool ALIGN_EPI = false, bool SP2 = false>
; __device__ __forceinline__ void gemm_phase(PG8_LAS unsigned char* lds, const Gemm g, const Sched& S, const Epi& E) {
;     ...
;         for (int t = 0; t < nt; t += 2) {
;     ...
;             PG8_LDA(At, 1, 1); PG8_STAGE(PG8_SB(1, 0), b3, voffB); PG8_STAGE(PG8_SB(1, 1), b3 + hstep, voffB); PG8_STAGE(PG8_SA(1, 0), a3, voffA);
;             PG8_WAIT_V(8); PG8_WAIT_L(0); PG8_BAR; PG8_MMA(1, 0, At, B0); PG8_MMA(1, 1, At, B1); PG8_BAR; PG8_SCHED;
	s_add_i32 s20, s45, s62
	v_lshl_add_u64 v[210:211], v[210:211], 0, s[24:25]
	s_mov_b32 m0, s20
	ds_read_b128 v[178:181], v169 offset:49152
	ds_read_b128 v[182:185], v169 offset:50176
	ds_read_b128 v[186:189], v169 offset:51200
	ds_read_b128 v[190:193], v169 offset:52224
	ds_read_b128 v[194:197], v169 offset:53248
	ds_read_b128 v[198:201], v169 offset:54272
	ds_read_b128 v[202:205], v169 offset:55296
	ds_read_b128 v[206:209], v169 offset:56320
	global_load_lds_dwordx4 v[210:211], off
	v_lshl_add_u64 v[210:211], v[212:213], 0, s[24:25]
	s_add_i32 m0, s20, 0x2000
	s_add_i32 s20, s46, s62
	global_load_lds_dwordx4 v[210:211], off
	s_mov_b32 m0, s20
	v_lshl_add_u64 v[210:211], v[214:215], 0, s[24:25]
	global_load_lds_dwordx4 v[210:211], off
	s_add_i32 m0, s20, 0x2000
	v_lshl_add_u64 v[210:211], v[218:219], 0, s[24:25]
	global_load_lds_dwordx4 v[210:211], off
	s_mov_b32 m0, s68
	v_lshl_add_u64 v[210:211], v[220:221], 0, s[24:25]
	global_load_lds_dwordx4 v[210:211], off
	s_mov_b32 m0, s69
	v_lshl_add_u64 v[210:211], v[222:223], 0, s[24:25]
	global_load_lds_dwordx4 v[210:211], off
	s_waitcnt vmcnt(8)
	s_waitcnt lgkmcnt(0)
	s_barrier
	s_setprio 1
	s_waitcnt lgkmcnt(0)
	v_mfma_f32_16x16x32_bf16 v[102:105], v[82:85], v[178:181], v[102:105]
	v_mfma_f32_16x16x32_bf16 v[98:101], v[138:141], v[178:181], v[98:101]
	v_mfma_f32_16x16x32_bf16 v[94:97], v[82:85], v[186:189], v[94:97]
	v_mfma_f32_16x16x32_bf16 v[90:93], v[138:141], v[186:189], v[90:93]
	v_mfma_f32_16x16x32_bf16 v[78:81], v[82:85], v[194:197], v[78:81]
	v_mfma_f32_16x16x32_bf16 v[74:77], v[138:141], v[194:197], v[74:77]
	v_mfma_f32_16x16x32_bf16 v[70:73], v[82:85], v[202:205], v[70:73]
	v_mfma_f32_16x16x32_bf16 v[66:69], v[138:141], v[202:205], v[66:69]
	v_mfma_f32_16x16x32_bf16 v[102:105], v[86:89], v[182:185], v[102:105]
	v_mfma_f32_16x16x32_bf16 v[98:101], v[142:145], v[182:185], v[98:101]
	v_mfma_f32_16x16x32_bf16 v[94:97], v[86:89], v[190:193], v[94:97]
	v_mfma_f32_16x16x32_bf16 v[90:93], v[142:145], v[190:193], v[90:93]
	v_mfma_f32_16x16x32_bf16 v[78:81], v[86:89], v[198:201], v[78:81]
	v_mfma_f32_16x16x32_bf16 v[74:77], v[142:145], v[198:201], v[74:77]
	v_mfma_f32_16x16x32_bf16 v[70:73], v[86:89], v[206:209], v[70:73]
	v_mfma_f32_16x16x32_bf16 v[66:69], v[142:145], v[206:209], v[66:69]
	s_setprio 0
	s_setprio 1
	v_mfma_f32_16x16x32_bf16 v[30:33], v[158:161], v[178:181], v[30:33]
	v_mfma_f32_16x16x32_bf16 v[26:29], v[170:173], v[178:181], v[26:29]
	v_mfma_f32_16x16x32_bf16 v[22:25], v[158:161], v[186:189], v[22:25]
	v_mfma_f32_16x16x32_bf16 v[18:21], v[170:173], v[186:189], v[18:21]
	v_mfma_f32_16x16x32_bf16 v[14:17], v[158:161], v[194:197], v[14:17]
	v_mfma_f32_16x16x32_bf16 v[10:13], v[170:173], v[194:197], v[10:13]
	v_mfma_f32_16x16x32_bf16 v[6:9], v[158:161], v[202:205], v[6:9]
	v_mfma_f32_16x16x32_bf16 v[2:5], v[170:173], v[202:205], v[2:5]
	v_mfma_f32_16x16x32_bf16 v[30:33], v[162:165], v[182:185], v[30:33]
	v_mfma_f32_16x16x32_bf16 v[26:29], v[174:177], v[182:185], v[26:29]
	v_mfma_f32_16x16x32_bf16 v[22:25], v[162:165], v[190:193], v[22:25]
	v_mfma_f32_16x16x32_bf16 v[18:21], v[174:177], v[190:193], v[18:21]
	v_mfma_f32_16x16x32_bf16 v[14:17], v[162:165], v[198:201], v[14:17]
	v_mfma_f32_16x16x32_bf16 v[10:13], v[174:177], v[198:201], v[10:13]
	v_mfma_f32_16x16x32_bf16 v[6:9], v[162:165], v[206:209], v[6:9]
	v_mfma_f32_16x16x32_bf16 v[2:5], v[174:177], v[206:209], v[2:5]
	s_setprio 0
	s_barrier
	s_add_u32 s16, s16, 0x100
	s_addc_u32 s17, s17, 0
	s_add_u32 s33, s33, 0x100
	s_addc_u32 s39, s39, 0
	s_cmp_ge_i32 s44, s67
	s_mov_b32 s20, s44
	s_cbranch_scc0 .LBB0_341
	s_movk_i32 s39, 0x5000

; #define PG8_STAGE(bufoff, gbase, voff) do { _Pragma("unroll") for (int _i = 0; _i < 2; ++_i) \
;         __builtin_amdgcn_global_load_lds((const unsigned*)((const char*)(gbase) + (voff)[_i]), (PG8_LAS unsigned*)(lds + (bufoff) + ldsw + _i * 8192), 16, 0, 0); } while (0)
; #define PG8_WAIT_V(n) asm volatile("s_waitcnt vmcnt(" #n ")" ::: "memory")
; #define PG8_BAR __builtin_amdgcn_s_barrier()
; template <class Epi, class Sched, bool ALIGN_EPI = false, bool SP2 = false>
; __device__ __forceinline__ void gemm_phase(PG8_LAS unsigned char* lds, const Gemm g, const Sched& S, const Epi& E) {
;     ...
;     for (int i = 0; i < 2; ++i) { int R, C; stage_rc(tid * 16 + i * 8192, R, C); const int Rb = Epi::PERM ? ((R & ~31) + perm32(R & 31)) : R;
;         voffA[i] = (unsigned)(R * K + C) * 2u; voffB[i] = (unsigned)(Rb * K + C) * 2u; }
;     const size_t kstep = (size_t)(BK * 2);
;     const size_t hstep = (size_t)HALF * K * 2;
;     const size_t tstep = 2 * hstep;
;     const unsigned ldsw = (unsigned)wid * 1024u;
;     const int aoff = lds_byte(wr * 64 + fr, fq * 8), boff = lds_byte(wc * 32 + fr, fq * 8);
;     ...
;         PG8_STAGE(PG8_SB(1, 0), cB + kstep, voffB); PG8_STAGE(PG8_SA(1, 0), cA + kstep, voffA); PG8_STAGE(PG8_SB(1, 1), cB + hstep + kstep, voffB);
;         PG8_WAIT_V(6); PG8_BAR;
.LBB0_509:
	s_add_i32 m0, s56, 0x18000
	v_lshl_add_u64 v[2:3], v[2:3], 0, s[24:25]
	s_waitcnt vmcnt(2)
	s_barrier
	global_load_lds_dwordx4 v[2:3], off
	v_lshl_add_u64 v[2:3], v[4:5], 0, s[24:25]
	s_add_i32 m0, s56, 0x1a000
	s_add_i32 s60, s56, 0x8000
	global_load_lds_dwordx4 v[2:3], off
	v_lshl_add_u64 v[2:3], v[10:11], 0, s[24:25]
	s_mov_b32 m0, s60
	s_add_i32 s61, s56, 0xa000
	global_load_lds_dwordx4 v[2:3], off
	v_lshl_add_u64 v[2:3], v[12:13], 0, s[24:25]
	s_mov_b32 m0, s61
	v_bfe_u32 v4, v14, 4, 2
	global_load_lds_dwordx4 v[2:3], off
	s_add_i32 m0, s56, 0x1c000
	v_lshl_add_u64 v[2:3], v[6:7], 0, s[24:25]
	global_load_lds_dwordx4 v[2:3], off
	v_lshl_add_u64 v[2:3], v[8:9], 0, s[24:25]
	s_add_i32 m0, s56, 0x1e000
	s_lshr_b32 s7, s7, 26
	global_load_lds_dwordx4 v[2:3], off
	v_and_b32_e32 v3, 15, v14
	s_add_i32 s7, s6, s7
	v_lshlrev_b32_e32 v2, 4, v4
	v_lshlrev_b32_e32 v5, 2, v14
	s_ashr_i32 s62, s7, 6
	v_lshl_or_b32 v183, s11, 6, v3
	v_lshl_or_b32 v3, v3, 6, v2
	s_lshl_b32 s7, s11, 13
	v_and_b32_e32 v5, 32, v5
	v_bitop3_b32 v6, v3, s7, v5 bitop3:0xde
	s_lshl_b32 s7, s9, 5
	s_and_b32 s7, s7, 0x60
	s_lshl_b32 s9, s7, 7
	v_bitop3_b32 v185, v3, s9, v5 bitop3:0xde
	v_add_u32_e32 v185, 0x10000, v185
	v_mov_b32_e32 v3, v1
	v_lshl_add_u64 v[160:161], s[88:89], 0, v[2:3]
	v_add_u32_e32 v2, v20, v18
	s_cmp_gt_i32 s6, 63
	v_add_lshl_u32 v2, v2, v19, 1
	s_waitcnt vmcnt(6)
	s_cselect_b64 s[44:45], -1, 0
	s_add_i32 s63, s62, -2
	v_lshl_add_u64 v[162:163], s[12:13], 0, v[2:3]
	v_add_u32_e32 v2, v17, v15
	s_cmpk_lt_u32 s8, 0x100
	v_add_lshl_u32 v2, v2, v16, 1
	s_cselect_b64 s[46:47], -1, 0
	s_ashr_i32 s11, s10, 31
	v_lshl_or_b32 v188, v4, 3, s7
	v_lshl_add_u64 v[164:165], s[12:13], 0, v[2:3]
	s_mov_b32 s64, 0
	v_add_u32_e32 v189, 0, v6
	s_barrier
	s_branch .LBB0_512

; #define PG8_STAGE(bufoff, gbase, voff) do { _Pragma("unroll") for (int _i = 0; _i < 2; ++_i) \
;         __builtin_amdgcn_global_load_lds((const unsigned*)((const char*)(gbase) + (voff)[_i]), (PG8_LAS unsigned*)(lds + (bufoff) + ldsw + _i * 8192), 16, 0, 0); } while (0)
; #define PG8_LDA(dst, b, h) do { _Pragma("unroll") for (int m = 0; m < 4; ++m) _Pragma("unroll") for (int k = 0; k < 2; ++k) dst[m][k] = *(const PG8_LAS bf16x8*)(lds + PG8_SA(b, h) + aoff + m * 2048 + k * 1024); } while (0)
; #define PG8_LDB(dst, b, h) do { _Pragma("unroll") for (int n = 0; n < 2; ++n) _Pragma("unroll") for (int k = 0; k < 2; ++k) dst[n][k] = *(const PG8_LAS bf16x8*)(lds + PG8_SB(b, h) + boff + n * 2048 + k * 1024); } while (0)
; #define PG8_WAIT_V(n) asm volatile("s_waitcnt vmcnt(" #n ")" ::: "memory")
; #define PG8_WAIT_L(n) asm volatile("s_waitcnt lgkmcnt(" #n ")" ::: "memory")
; #define PG8_BAR __builtin_amdgcn_s_barrier()
; #define PG8_SCHED __builtin_amdgcn_sched_barrier(0)
; template <class Epi, class Sched, bool ALIGN_EPI = false, bool SP2 = false>
; __device__ __forceinline__ void gemm_phase(PG8_LAS unsigned char* lds, const Gemm g, const Sched& S, const Epi& E) {
;     ...
;         const bool has_next = S.next(ui + 1, nxt);
;         const char* nA = has_next ? (const char*)g.A + (size_t)nxt.pm * tstep : cA; const char* nB = has_next ? (const char*)g.Bt + (size_t)nxt.pn * tstep : cB;
;         for (int t = 0; t < nt; t += 2) {
;             const bool last = (t == nt - 2);
;             const char* a1 = cA + (size_t)(t + 1) * kstep;
;             const char* a2 = last ? nA : cA + (size_t)(t + 2) * kstep; const char* b2 = last ? nB : cB + (size_t)(t + 2) * kstep;
;             const char* a3 = a2 + kstep; const char* b3 = b2 + kstep;
;             if (last && has_next) S.a_ready(nxt);
;             if constexpr (SP2) {
;             PG8_LDB(B0, 0, 0); PG8_LDB(B1, 0, 1); PG8_SCHED; PG8_LDA(At, 0, 0); PG8_STAGE(PG8_SA(1, 1), a1 + hstep, voffA);
;             PG8_WAIT_V(8); PG8_WAIT_L(0); PG8_BAR; PG8_MMA(0, 0, At, B0); PG8_MMA(0, 1, At, B1); PG8_BAR; PG8_SCHED;
;             PG8_LDA(At, 0, 1); PG8_STAGE(PG8_SB(0, 0), b2, voffB); PG8_STAGE(PG8_SB(0, 1), b2 + hstep, voffB); PG8_STAGE(PG8_SA(0, 0), a2, voffA);
;             PG8_WAIT_V(8); PG8_WAIT_L(0); PG8_BAR; PG8_MMA(1, 0, At, B0); PG8_MMA(1, 1, At, B1); PG8_BAR; PG8_SCHED;
.LBB0_520:
	s_add_i32 s69, s20, 2
	s_add_u32 s70, s8, 0x80
	s_addc_u32 s21, s9, 0
	s_add_i32 s72, 0, 0x10000
	s_cmp_eq_u32 s63, s20
	s_cselect_b32 s21, s49, s21
	s_cselect_b32 s20, s48, s70
	s_cselect_b32 s71, s51, s53
	s_cselect_b32 s70, s50, s52
	s_add_i32 s73, 0, 0x14000
	ds_read_b128 v[130:133], v185
	ds_read_b128 v[134:137], v185 offset:1024
	ds_read_b128 v[138:141], v185 offset:2048
	ds_read_b128 v[142:145], v185 offset:3072
	ds_read_b128 v[146:149], v185 offset:16384
	ds_read_b128 v[150:153], v185 offset:17408
	ds_read_b128 v[166:169], v185 offset:18432
	ds_read_b128 v[170:173], v185 offset:19456
	v_lshl_add_u64 v[186:187], s[8:9], 0, v[162:163]
	s_add_i32 m0, s56, 0xc000
	ds_read_b128 v[174:177], v189
	ds_read_b128 v[178:181], v189 offset:1024
	ds_read_b128 v[190:193], v189 offset:2048
	ds_read_b128 v[194:197], v189 offset:3072
	ds_read_b128 v[198:201], v189 offset:4096
	ds_read_b128 v[202:205], v189 offset:5120
	ds_read_b128 v[206:209], v189 offset:6144
	ds_read_b128 v[210:213], v189 offset:7168
	global_load_lds_dwordx4 v[186:187], off
	s_add_i32 m0, s56, 0xe000
	v_lshl_add_u64 v[186:187], s[8:9], 0, v[164:165]
	global_load_lds_dwordx4 v[186:187], off
	s_waitcnt vmcnt(8)
	s_waitcnt lgkmcnt(0)
	s_barrier
	s_setprio 1
	s_waitcnt lgkmcnt(0)
	v_mfma_f32_16x16x32_bf16 v[126:129], v[130:133], v[174:177], v[126:129]
	v_mfma_f32_16x16x32_bf16 v[122:125], v[138:141], v[174:177], v[122:125]
	v_mfma_f32_16x16x32_bf16 v[110:113], v[130:133], v[190:193], v[110:113]
	v_mfma_f32_16x16x32_bf16 v[106:109], v[138:141], v[190:193], v[106:109]
	v_mfma_f32_16x16x32_bf16 v[94:97], v[130:133], v[198:201], v[94:97]
	v_mfma_f32_16x16x32_bf16 v[90:93], v[138:141], v[198:201], v[90:93]
	v_mfma_f32_16x16x32_bf16 v[78:81], v[130:133], v[206:209], v[78:81]
	v_mfma_f32_16x16x32_bf16 v[74:77], v[138:141], v[206:209], v[74:77]
	v_mfma_f32_16x16x32_bf16 v[126:129], v[134:137], v[178:181], v[126:129]
	v_mfma_f32_16x16x32_bf16 v[122:125], v[142:145], v[178:181], v[122:125]
	v_mfma_f32_16x16x32_bf16 v[110:113], v[134:137], v[194:197], v[110:113]
	v_mfma_f32_16x16x32_bf16 v[106:109], v[142:145], v[194:197], v[106:109]
	v_mfma_f32_16x16x32_bf16 v[94:97], v[134:137], v[202:205], v[94:97]
	v_mfma_f32_16x16x32_bf16 v[90:93], v[142:145], v[202:205], v[90:93]
	v_mfma_f32_16x16x32_bf16 v[78:81], v[134:137], v[210:213], v[78:81]
	v_mfma_f32_16x16x32_bf16 v[74:77], v[142:145], v[210:213], v[74:77]
	s_setprio 0
	s_setprio 1
	v_mfma_f32_16x16x32_bf16 v[118:121], v[146:149], v[174:177], v[118:121]
	v_mfma_f32_16x16x32_bf16 v[114:117], v[166:169], v[174:177], v[114:117]
	v_mfma_f32_16x16x32_bf16 v[102:105], v[146:149], v[190:193], v[102:105]
	v_mfma_f32_16x16x32_bf16 v[98:101], v[166:169], v[190:193], v[98:101]
	v_mfma_f32_16x16x32_bf16 v[86:89], v[146:149], v[198:201], v[86:89]
	v_mfma_f32_16x16x32_bf16 v[82:85], v[166:169], v[198:201], v[82:85]
	v_mfma_f32_16x16x32_bf16 v[70:73], v[146:149], v[206:209], v[70:73]
	v_mfma_f32_16x16x32_bf16 v[66:69], v[166:169], v[206:209], v[66:69]
	v_mfma_f32_16x16x32_bf16 v[118:121], v[150:153], v[178:181], v[118:121]
	v_mfma_f32_16x16x32_bf16 v[114:117], v[170:173], v[178:181], v[114:117]
	v_mfma_f32_16x16x32_bf16 v[102:105], v[150:153], v[194:197], v[102:105]
	v_mfma_f32_16x16x32_bf16 v[98:101], v[170:173], v[194:197], v[98:101]
	v_mfma_f32_16x16x32_bf16 v[86:89], v[150:153], v[202:205], v[86:89]
	v_mfma_f32_16x16x32_bf16 v[82:85], v[170:173], v[202:205], v[82:85]
	v_mfma_f32_16x16x32_bf16 v[70:73], v[150:153], v[210:213], v[70:73]
	v_mfma_f32_16x16x32_bf16 v[66:69], v[170:173], v[210:213], v[66:69]
	s_setprio 0
	s_barrier
	s_add_i32 s72, s72, s30
	v_lshl_add_u64 v[186:187], s[70:71], 0, v[0:1]
	s_mov_b32 m0, s72
	ds_read_b128 v[174:177], v189 offset:16384
	ds_read_b128 v[178:181], v189 offset:17408
	ds_read_b128 v[190:193], v189 offset:18432
	ds_read_b128 v[194:197], v189 offset:19456
	ds_read_b128 v[198:201], v189 offset:20480
	ds_read_b128 v[202:205], v189 offset:21504
	ds_read_b128 v[206:209], v189 offset:22528
	ds_read_b128 v[210:213], v189 offset:23552
	global_load_lds_dwordx4 v[186:187], off
	s_add_i32 m0, s72, 0x2000
	v_lshl_add_u64 v[214:215], s[70:71], 0, v[154:155]
	s_add_u32 s70, s70, s12
	s_addc_u32 s71, s71, s13
	s_add_i32 s72, s73, s30
	global_load_lds_dwordx4 v[214:215], off
	v_lshl_add_u64 v[218:219], s[70:71], 0, v[0:1]
	s_mov_b32 m0, s72
	v_lshl_add_u64 v[220:221], s[70:71], 0, v[154:155]
	global_load_lds_dwordx4 v[218:219], off
	s_add_i32 m0, s72, 0x2000
	v_lshl_add_u64 v[222:223], s[20:21], 0, v[158:159]
	global_load_lds_dwordx4 v[220:221], off
	s_mov_b32 m0, s56
	v_lshl_add_u64 v[224:225], s[20:21], 0, v[156:157]
	global_load_lds_dwordx4 v[222:223], off
	s_mov_b32 m0, s57
	s_nop 0
	global_load_lds_dwordx4 v[224:225], off
	s_waitcnt vmcnt(8)
	s_waitcnt lgkmcnt(0)
	s_barrier
; #define PG8_STAGE(bufoff, gbase, voff) do { _Pragma("unroll") for (int _i = 0; _i < 2; ++_i) \
;         __builtin_amdgcn_global_load_lds((const unsigned*)((const char*)(gbase) + (voff)[_i]), (PG8_LAS unsigned*)(lds + (bufoff) + ldsw + _i * 8192), 16, 0, 0); } while (0)
; #define PG8_LDA(dst, b, h) do { _Pragma("unroll") for (int m = 0; m < 4; ++m) _Pragma("unroll") for (int k = 0; k < 2; ++k) dst[m][k] = *(const PG8_LAS bf16x8*)(lds + PG8_SA(b, h) + aoff + m * 2048 + k * 1024); } while (0)
; #define PG8_LDB(dst, b, h) do { _Pragma("unroll") for (int n = 0; n < 2; ++n) _Pragma("unroll") for (int k = 0; k < 2; ++k) dst[n][k] = *(const PG8_LAS bf16x8*)(lds + PG8_SB(b, h) + boff + n * 2048 + k * 1024); } while (0)
; #define PG8_MMA(ai, bj, At, Bt) do { __builtin_amdgcn_s_setprio(1); _Pragma("unroll") for (int m = 0; m < 4; ++m) _Pragma("unroll") for (int n = 0; n < 2; ++n) _Pragma("unroll") for (int k = 0; k < 2; ++k) \
;         acc[ai][bj][m][n] = __builtin_amdgcn_mfma_f32_16x16x32_bf16(Bt[n][k], At[m][k], acc[ai][bj][m][n], 0, 0, 0); __builtin_amdgcn_s_setprio(0); } while (0)
; #define PG8_WAIT_V(n) asm volatile("s_waitcnt vmcnt(" #n ")" ::: "memory")
; #define PG8_WAIT_L(n) asm volatile("s_waitcnt lgkmcnt(" #n ")" ::: "memory")
; #define PG8_BAR __builtin_amdgcn_s_barrier()
; #define PG8_SCHED __builtin_amdgcn_sched_barrier(0)
; template <class Epi, class Sched, bool ALIGN_EPI = false, bool SP2 = false>
; __device__ __forceinline__ void gemm_phase(PG8_LAS unsigned char* lds, const Gemm g, const Sched& S, const Epi& E) {
;     ...
;             PG8_WAIT_V(8); PG8_WAIT_L(0); PG8_BAR; PG8_MMA(1, 0, At, B0); PG8_MMA(1, 1, At, B1); PG8_BAR; PG8_SCHED;
;             PG8_LDB(B0, 1, 0); PG8_LDB(B1, 1, 1); PG8_SCHED; PG8_LDA(At, 1, 0); PG8_STAGE(PG8_SA(0, 1), a2 + hstep, voffA);
;             PG8_WAIT_V(8); PG8_WAIT_L(0); PG8_BAR; PG8_MMA(0, 0, At, B0); PG8_MMA(0, 1, At, B1); PG8_BAR; PG8_SCHED;
	s_setprio 1
	s_waitcnt lgkmcnt(0)
	v_mfma_f32_16x16x32_bf16 v[62:65], v[130:133], v[174:177], v[62:65]
	v_mfma_f32_16x16x32_bf16 v[58:61], v[138:141], v[174:177], v[58:61]
	v_mfma_f32_16x16x32_bf16 v[46:49], v[130:133], v[190:193], v[46:49]
	v_mfma_f32_16x16x32_bf16 v[42:45], v[138:141], v[190:193], v[42:45]
	v_mfma_f32_16x16x32_bf16 v[30:33], v[130:133], v[198:201], v[30:33]
	v_mfma_f32_16x16x32_bf16 v[26:29], v[138:141], v[198:201], v[26:29]
	v_mfma_f32_16x16x32_bf16 v[14:17], v[130:133], v[206:209], v[14:17]
	v_mfma_f32_16x16x32_bf16 v[10:13], v[138:141], v[206:209], v[10:13]
	v_mfma_f32_16x16x32_bf16 v[62:65], v[134:137], v[178:181], v[62:65]
	v_mfma_f32_16x16x32_bf16 v[58:61], v[142:145], v[178:181], v[58:61]
	v_mfma_f32_16x16x32_bf16 v[46:49], v[134:137], v[194:197], v[46:49]
	v_mfma_f32_16x16x32_bf16 v[42:45], v[142:145], v[194:197], v[42:45]
	v_mfma_f32_16x16x32_bf16 v[30:33], v[134:137], v[202:205], v[30:33]
	v_mfma_f32_16x16x32_bf16 v[26:29], v[142:145], v[202:205], v[26:29]
	v_mfma_f32_16x16x32_bf16 v[14:17], v[134:137], v[210:213], v[14:17]
	v_mfma_f32_16x16x32_bf16 v[10:13], v[142:145], v[210:213], v[10:13]
	s_setprio 0
	s_setprio 1
	v_mfma_f32_16x16x32_bf16 v[54:57], v[146:149], v[174:177], v[54:57]
	v_mfma_f32_16x16x32_bf16 v[50:53], v[166:169], v[174:177], v[50:53]
	v_mfma_f32_16x16x32_bf16 v[38:41], v[146:149], v[190:193], v[38:41]
	v_mfma_f32_16x16x32_bf16 v[34:37], v[166:169], v[190:193], v[34:37]
	v_mfma_f32_16x16x32_bf16 v[22:25], v[146:149], v[198:201], v[22:25]
	v_mfma_f32_16x16x32_bf16 v[18:21], v[166:169], v[198:201], v[18:21]
	v_mfma_f32_16x16x32_bf16 v[6:9], v[146:149], v[206:209], v[6:9]
	v_mfma_f32_16x16x32_bf16 v[2:5], v[166:169], v[206:209], v[2:5]
	v_mfma_f32_16x16x32_bf16 v[54:57], v[150:153], v[178:181], v[54:57]
	v_mfma_f32_16x16x32_bf16 v[50:53], v[170:173], v[178:181], v[50:53]
	v_mfma_f32_16x16x32_bf16 v[38:41], v[150:153], v[194:197], v[38:41]
	v_mfma_f32_16x16x32_bf16 v[34:37], v[170:173], v[194:197], v[34:37]
	v_mfma_f32_16x16x32_bf16 v[22:25], v[150:153], v[202:205], v[22:25]
	v_mfma_f32_16x16x32_bf16 v[18:21], v[170:173], v[202:205], v[18:21]
	v_mfma_f32_16x16x32_bf16 v[6:9], v[150:153], v[210:213], v[6:9]
	v_mfma_f32_16x16x32_bf16 v[2:5], v[170:173], v[210:213], v[2:5]
	s_setprio 0
	s_barrier
	s_add_i32 s70, 0, 0x18000
	s_add_i32 s71, 0, 0x1c000
	ds_read_b128 v[130:133], v185 offset:32768
	ds_read_b128 v[134:137], v185 offset:33792
	ds_read_b128 v[138:141], v185 offset:34816
	ds_read_b128 v[142:145], v185 offset:35840
	ds_read_b128 v[146:149], v185 offset:49152
	ds_read_b128 v[150:153], v185 offset:50176
	ds_read_b128 v[166:169], v185 offset:51200
	ds_read_b128 v[170:173], v185 offset:52224
	s_add_u32 s20, s20, s12
	s_addc_u32 s21, s21, s13
	s_mov_b32 m0, s58
	v_lshl_add_u64 v[226:227], s[20:21], 0, v[158:159]
	ds_read_b128 v[174:177], v189 offset:32768
	ds_read_b128 v[178:181], v189 offset:33792
	ds_read_b128 v[190:193], v189 offset:34816
	ds_read_b128 v[194:197], v189 offset:35840
	ds_read_b128 v[198:201], v189 offset:36864
	ds_read_b128 v[202:205], v189 offset:37888
	ds_read_b128 v[206:209], v189 offset:38912
	ds_read_b128 v[210:213], v189 offset:39936
	global_load_lds_dwordx4 v[226:227], off
	s_mov_b32 m0, s59
	v_lshl_add_u64 v[226:227], s[20:21], 0, v[156:157]
	global_load_lds_dwordx4 v[226:227], off
	s_waitcnt vmcnt(8)
	s_waitcnt lgkmcnt(0)
	s_barrier
	s_setprio 1
	s_waitcnt lgkmcnt(0)
	v_mfma_f32_16x16x32_bf16 v[126:129], v[130:133], v[174:177], v[126:129]
	v_mfma_f32_16x16x32_bf16 v[122:125], v[138:141], v[174:177], v[122:125]
	v_mfma_f32_16x16x32_bf16 v[110:113], v[130:133], v[190:193], v[110:113]
	v_mfma_f32_16x16x32_bf16 v[106:109], v[138:141], v[190:193], v[106:109]
	v_mfma_f32_16x16x32_bf16 v[94:97], v[130:133], v[198:201], v[94:97]
	v_mfma_f32_16x16x32_bf16 v[90:93], v[138:141], v[198:201], v[90:93]
	v_mfma_f32_16x16x32_bf16 v[78:81], v[130:133], v[206:209], v[78:81]
	v_mfma_f32_16x16x32_bf16 v[74:77], v[138:141], v[206:209], v[74:77]
	v_mfma_f32_16x16x32_bf16 v[126:129], v[134:137], v[178:181], v[126:129]
	v_mfma_f32_16x16x32_bf16 v[122:125], v[142:145], v[178:181], v[122:125]
	v_mfma_f32_16x16x32_bf16 v[110:113], v[134:137], v[194:197], v[110:113]
	v_mfma_f32_16x16x32_bf16 v[106:109], v[142:145], v[194:197], v[106:109]
	v_mfma_f32_16x16x32_bf16 v[94:97], v[134:137], v[202:205], v[94:97]
	v_mfma_f32_16x16x32_bf16 v[90:93], v[142:145], v[202:205], v[90:93]
	v_mfma_f32_16x16x32_bf16 v[78:81], v[134:137], v[210:213], v[78:81]
	v_mfma_f32_16x16x32_bf16 v[74:77], v[142:145], v[210:213], v[74:77]
	s_setprio 0
	s_setprio 1
	v_mfma_f32_16x16x32_bf16 v[118:121], v[146:149], v[174:177], v[118:121]
	v_mfma_f32_16x16x32_bf16 v[114:117], v[166:169], v[174:177], v[114:117]
	v_mfma_f32_16x16x32_bf16 v[102:105], v[146:149], v[190:193], v[102:105]
	v_mfma_f32_16x16x32_bf16 v[98:101], v[166:169], v[190:193], v[98:101]
	v_mfma_f32_16x16x32_bf16 v[86:89], v[146:149], v[198:201], v[86:89]
	v_mfma_f32_16x16x32_bf16 v[82:85], v[166:169], v[198:201], v[82:85]
	v_mfma_f32_16x16x32_bf16 v[70:73], v[146:149], v[206:209], v[70:73]
	v_mfma_f32_16x16x32_bf16 v[66:69], v[166:169], v[206:209], v[66:69]
	v_mfma_f32_16x16x32_bf16 v[118:121], v[150:153], v[178:181], v[118:121]
	v_mfma_f32_16x16x32_bf16 v[114:117], v[170:173], v[178:181], v[114:117]
	v_mfma_f32_16x16x32_bf16 v[102:105], v[150:153], v[194:197], v[102:105]
	v_mfma_f32_16x16x32_bf16 v[98:101], v[170:173], v[194:197], v[98:101]
	v_mfma_f32_16x16x32_bf16 v[86:89], v[150:153], v[202:205], v[86:89]
	v_mfma_f32_16x16x32_bf16 v[82:85], v[170:173], v[202:205], v[82:85]
	v_mfma_f32_16x16x32_bf16 v[70:73], v[150:153], v[210:213], v[70:73]
	v_mfma_f32_16x16x32_bf16 v[66:69], v[170:173], v[210:213], v[66:69]
	s_setprio 0
	s_barrier
; #define PG8_STAGE(bufoff, gbase, voff) do { _Pragma("unroll") for (int _i = 0; _i < 2; ++_i) \
;         __builtin_amdgcn_global_load_lds((const unsigned*)((const char*)(gbase) + (voff)[_i]), (PG8_LAS unsigned*)(lds + (bufoff) + ldsw + _i * 8192), 16, 0, 0); } while (0)
; #define PG8_LDA(dst, b, h) do { _Pragma("unroll") for (int m = 0; m < 4; ++m) _Pragma("unroll") for (int k = 0; k < 2; ++k) dst[m][k] = *(const PG8_LAS bf16x8*)(lds + PG8_SA(b, h) + aoff + m * 2048 + k * 1024); } while (0)
; #define PG8_MMA(ai, bj, At, Bt) do { __builtin_amdgcn_s_setprio(1); _Pragma("unroll") for (int m = 0; m < 4; ++m) _Pragma("unroll") for (int n = 0; n < 2; ++n) _Pragma("unroll") for (int k = 0; k < 2; ++k) \
;         acc[ai][bj][m][n] = __builtin_amdgcn_mfma_f32_16x16x32_bf16(Bt[n][k], At[m][k], acc[ai][bj][m][n], 0, 0, 0); __builtin_amdgcn_s_setprio(0); } while (0)
; #define PG8_WAIT_V(n) asm volatile("s_waitcnt vmcnt(" #n ")" ::: "memory")
; #define PG8_WAIT_L(n) asm volatile("s_waitcnt lgkmcnt(" #n ")" ::: "memory")
; #define PG8_BAR __builtin_amdgcn_s_barrier()
; #define PG8_SCHED __builtin_amdgcn_sched_barrier(0)
; template <class Epi, class Sched, bool ALIGN_EPI = false, bool SP2 = false>
; __device__ __forceinline__ void gemm_phase(PG8_LAS unsigned char* lds, const Gemm g, const Sched& S, const Epi& E) {
;     ...
;         for (int t = 0; t < nt; t += 2) {
;     ...
;             PG8_LDA(At, 1, 1); PG8_STAGE(PG8_SB(1, 0), b3, voffB); PG8_STAGE(PG8_SB(1, 1), b3 + hstep, voffB); PG8_STAGE(PG8_SA(1, 0), a3, voffA);
;             PG8_WAIT_V(8); PG8_WAIT_L(0); PG8_BAR; PG8_MMA(1, 0, At, B0); PG8_MMA(1, 1, At, B1); PG8_BAR; PG8_SCHED;
	s_add_i32 s20, s70, s30
	v_lshl_add_u64 v[186:187], v[186:187], 0, s[24:25]
	s_mov_b32 m0, s20
	ds_read_b128 v[174:177], v189 offset:49152
	ds_read_b128 v[178:181], v189 offset:50176
	ds_read_b128 v[190:193], v189 offset:51200
	ds_read_b128 v[194:197], v189 offset:52224
	ds_read_b128 v[198:201], v189 offset:53248
	ds_read_b128 v[202:205], v189 offset:54272
	ds_read_b128 v[206:209], v189 offset:55296
	ds_read_b128 v[210:213], v189 offset:56320
	global_load_lds_dwordx4 v[186:187], off
	v_lshl_add_u64 v[186:187], v[214:215], 0, s[24:25]
	s_add_i32 m0, s20, 0x2000
	s_add_i32 s20, s71, s30
	global_load_lds_dwordx4 v[186:187], off
	s_mov_b32 m0, s20
	v_lshl_add_u64 v[186:187], v[218:219], 0, s[24:25]
	global_load_lds_dwordx4 v[186:187], off
	s_add_i32 m0, s20, 0x2000
	v_lshl_add_u64 v[186:187], v[220:221], 0, s[24:25]
	global_load_lds_dwordx4 v[186:187], off
	s_mov_b32 m0, s60
	v_lshl_add_u64 v[186:187], v[222:223], 0, s[24:25]
	global_load_lds_dwordx4 v[186:187], off
	s_mov_b32 m0, s61
	v_lshl_add_u64 v[186:187], v[224:225], 0, s[24:25]
	global_load_lds_dwordx4 v[186:187], off
	s_waitcnt vmcnt(8)
	s_waitcnt lgkmcnt(0)
	s_barrier
	s_setprio 1
	s_waitcnt lgkmcnt(0)
	v_mfma_f32_16x16x32_bf16 v[62:65], v[130:133], v[174:177], v[62:65]
	v_mfma_f32_16x16x32_bf16 v[58:61], v[138:141], v[174:177], v[58:61]
	v_mfma_f32_16x16x32_bf16 v[46:49], v[130:133], v[190:193], v[46:49]
	v_mfma_f32_16x16x32_bf16 v[42:45], v[138:141], v[190:193], v[42:45]
	v_mfma_f32_16x16x32_bf16 v[30:33], v[130:133], v[198:201], v[30:33]
	v_mfma_f32_16x16x32_bf16 v[26:29], v[138:141], v[198:201], v[26:29]
	v_mfma_f32_16x16x32_bf16 v[14:17], v[130:133], v[206:209], v[14:17]
	v_mfma_f32_16x16x32_bf16 v[10:13], v[138:141], v[206:209], v[10:13]
	v_mfma_f32_16x16x32_bf16 v[62:65], v[134:137], v[178:181], v[62:65]
	v_mfma_f32_16x16x32_bf16 v[58:61], v[142:145], v[178:181], v[58:61]
	v_mfma_f32_16x16x32_bf16 v[46:49], v[134:137], v[194:197], v[46:49]
	v_mfma_f32_16x16x32_bf16 v[42:45], v[142:145], v[194:197], v[42:45]
	v_mfma_f32_16x16x32_bf16 v[30:33], v[134:137], v[202:205], v[30:33]
	v_mfma_f32_16x16x32_bf16 v[26:29], v[142:145], v[202:205], v[26:29]
	v_mfma_f32_16x16x32_bf16 v[14:17], v[134:137], v[210:213], v[14:17]
	v_mfma_f32_16x16x32_bf16 v[10:13], v[142:145], v[210:213], v[10:13]
	s_setprio 0
	s_setprio 1
	v_mfma_f32_16x16x32_bf16 v[54:57], v[146:149], v[174:177], v[54:57]
	v_mfma_f32_16x16x32_bf16 v[50:53], v[166:169], v[174:177], v[50:53]
	v_mfma_f32_16x16x32_bf16 v[38:41], v[146:149], v[190:193], v[38:41]
	v_mfma_f32_16x16x32_bf16 v[34:37], v[166:169], v[190:193], v[34:37]
	v_mfma_f32_16x16x32_bf16 v[22:25], v[146:149], v[198:201], v[22:25]
	v_mfma_f32_16x16x32_bf16 v[18:21], v[166:169], v[198:201], v[18:21]
	v_mfma_f32_16x16x32_bf16 v[6:9], v[146:149], v[206:209], v[6:9]
	v_mfma_f32_16x16x32_bf16 v[2:5], v[166:169], v[206:209], v[2:5]
	v_mfma_f32_16x16x32_bf16 v[54:57], v[150:153], v[178:181], v[54:57]
	v_mfma_f32_16x16x32_bf16 v[50:53], v[170:173], v[178:181], v[50:53]
	v_mfma_f32_16x16x32_bf16 v[38:41], v[150:153], v[194:197], v[38:41]
	v_mfma_f32_16x16x32_bf16 v[34:37], v[170:173], v[194:197], v[34:37]
	v_mfma_f32_16x16x32_bf16 v[22:25], v[150:153], v[202:205], v[22:25]
	v_mfma_f32_16x16x32_bf16 v[18:21], v[170:173], v[202:205], v[18:21]
	v_mfma_f32_16x16x32_bf16 v[6:9], v[150:153], v[210:213], v[6:9]
	v_mfma_f32_16x16x32_bf16 v[2:5], v[170:173], v[210:213], v[2:5]
	s_setprio 0
	s_barrier
	s_add_u32 s8, s8, 0x100
	s_addc_u32 s9, s9, 0
	s_add_u32 s52, s52, 0x100
	s_addc_u32 s53, s53, 0
	s_cmp_ge_i32 s69, s62
	s_mov_b32 s20, s69
	s_cbranch_scc0 .LBB0_520

; #define PG8_STAGE(bufoff, gbase, voff) do { _Pragma("unroll") for (int _i = 0; _i < 2; ++_i) \
;         __builtin_amdgcn_global_load_lds((const unsigned*)((const char*)(gbase) + (voff)[_i]), (PG8_LAS unsigned*)(lds + (bufoff) + ldsw + _i * 8192), 16, 0, 0); } while (0)
; #define PG8_WAIT_V(n) asm volatile("s_waitcnt vmcnt(" #n ")" ::: "memory")
; #define PG8_BAR __builtin_amdgcn_s_barrier()
; template <class Epi, class Sched, bool ALIGN_EPI = false, bool SP2 = false>
; __device__ __forceinline__ void gemm_phase(PG8_LAS unsigned char* lds, const Gemm g, const Sched& S, const Epi& E) {
;     ...
;     for (int i = 0; i < 2; ++i) { int R, C; stage_rc(tid * 16 + i * 8192, R, C); const int Rb = Epi::PERM ? ((R & ~31) + perm32(R & 31)) : R;
;         voffA[i] = (unsigned)(R * K + C) * 2u; voffB[i] = (unsigned)(Rb * K + C) * 2u; }
;     const size_t kstep = (size_t)(BK * 2);
;     const size_t hstep = (size_t)HALF * K * 2;
;     const size_t tstep = 2 * hstep;
;     const unsigned ldsw = (unsigned)wid * 1024u;
;     const int aoff = lds_byte(wr * 64 + fr, fq * 8), boff = lds_byte(wc * 32 + fr, fq * 8);
;     ...
;         PG8_STAGE(PG8_SB(1, 0), cB + kstep, voffB); PG8_STAGE(PG8_SA(1, 0), cA + kstep, voffA); PG8_STAGE(PG8_SB(1, 1), cB + hstep + kstep, voffB);
;         PG8_WAIT_V(6); PG8_BAR;
.LBB0_559:
	s_add_i32 m0, s64, 0x18000
	v_lshl_add_u64 v[2:3], v[2:3], 0, s[24:25]
	s_waitcnt vmcnt(2)
	s_barrier
	global_load_lds_dwordx4 v[2:3], off
	v_lshl_add_u64 v[2:3], v[4:5], 0, s[24:25]
	s_add_i32 m0, s64, 0x1a000
	s_add_i32 s39, s64, 0x8000
	global_load_lds_dwordx4 v[2:3], off
	v_lshl_add_u64 v[2:3], v[10:11], 0, s[24:25]
	s_mov_b32 m0, s39
	s_add_i32 s65, s64, 0xa000
	global_load_lds_dwordx4 v[2:3], off
	v_lshl_add_u64 v[2:3], v[12:13], 0, s[24:25]
	s_mov_b32 m0, s65
	s_lshr_b32 s9, s9, 26
	global_load_lds_dwordx4 v[2:3], off
	s_add_i32 m0, s64, 0x1c000
	v_lshl_add_u64 v[2:3], v[6:7], 0, s[24:25]
	global_load_lds_dwordx4 v[2:3], off
	v_lshl_add_u64 v[2:3], v[8:9], 0, s[24:25]
	s_add_i32 m0, s64, 0x1e000
	s_add_i32 s9, s8, s9
	global_load_lds_dwordx4 v[2:3], off
	v_bfe_u32 v2, v14, 4, 2
	v_and_b32_e32 v3, 15, v14
	v_lshlrev_b32_e32 v4, 4, v2
	v_lshl_or_b32 v217, s11, 6, v3
	v_lshl_or_b32 v3, v3, 6, v4
	v_lshlrev_b32_e32 v4, 2, v14
	s_and_b32 s66, s10, 3
	s_ashr_i32 s67, s9, 6
	s_lshl_b32 s9, s11, 13
	v_and_b32_e32 v4, 32, v4
	v_bitop3_b32 v5, v3, s9, v4 bitop3:0xde
	s_lshl_b32 s9, s66, 12
	s_cmp_gt_i32 s8, 63
	s_cselect_b64 s[50:51], -1, 0
	s_add_i32 s68, s67, -2
	s_cmpk_lt_u32 s45, 0x100
	s_cselect_b64 s[52:53], -1, 0
	s_ashr_i32 s45, s44, 31
	s_lshl_b32 s69, s58, 4
	s_lshl_b32 s70, s58, 3
	s_cmp_lg_u64 s[6:7], 0
	s_cselect_b64 s[54:55], -1, 0
	s_cmp_eq_u64 s[6:7], 0
	s_cselect_b32 s57, s13, s7
	s_cselect_b32 s56, s12, s6
	s_abs_i32 s71, s70
	v_bitop3_b32 v246, v3, s9, v4 bitop3:0xde
	v_add_u32_e32 v246, 0x10000, v246
	v_cvt_f32_u32_e32 v3, s71
	v_lshlrev_b32_e32 v4, 2, v2
	v_cmp_eq_u32_e64 s[6:7], 0, v2
	s_sub_i32 s8, 0, s71
	v_rcp_iflag_f32_e32 v3, v3
	s_waitcnt vmcnt(6)
	v_cndmask_b32_e64 v220, 1.0, 0.5, s[78:79]
	v_lshl_or_b32 v243, s66, 5, v4
	v_mul_f32_e32 v2, 0x4f7ffffe, v3
	v_cvt_u32_f32_e32 v2, v2
	s_mov_b32 s72, 0
	v_mov_b32_e32 v222, v220
	v_mov_b32_e32 v223, v220
	v_readfirstlane_b32 s9, v2
	s_mul_i32 s8, s8, s9
	s_mul_hi_u32 s8, s9, s8
	s_bfe_i32 s73, s58, 0x1001c
	s_add_i32 s74, s9, s8
	v_lshl_add_u64 v[224:225], s[46:47], 0, v[0:1]
	v_lshl_add_u64 v[226:227], s[46:47], 0, v[218:219]
	v_add_u32_e32 v249, 0, v5
	s_barrier
	s_branch .LBB0_562

; #define PG8_STAGE(bufoff, gbase, voff) do { _Pragma("unroll") for (int _i = 0; _i < 2; ++_i) \
;         __builtin_amdgcn_global_load_lds((const unsigned*)((const char*)(gbase) + (voff)[_i]), (PG8_LAS unsigned*)(lds + (bufoff) + ldsw + _i * 8192), 16, 0, 0); } while (0)
; #define PG8_LDA(dst, b, h) do { _Pragma("unroll") for (int m = 0; m < 4; ++m) _Pragma("unroll") for (int k = 0; k < 2; ++k) dst[m][k] = *(const PG8_LAS bf16x8*)(lds + PG8_SA(b, h) + aoff + m * 2048 + k * 1024); } while (0)
; #define PG8_LDB(dst, b, h) do { _Pragma("unroll") for (int n = 0; n < 2; ++n) _Pragma("unroll") for (int k = 0; k < 2; ++k) dst[n][k] = *(const PG8_LAS bf16x8*)(lds + PG8_SB(b, h) + boff + n * 2048 + k * 1024); } while (0)
; #define PG8_WAIT_V(n) asm volatile("s_waitcnt vmcnt(" #n ")" ::: "memory")
; #define PG8_WAIT_L(n) asm volatile("s_waitcnt lgkmcnt(" #n ")" ::: "memory")
; #define PG8_BAR __builtin_amdgcn_s_barrier()
; #define PG8_SCHED __builtin_amdgcn_sched_barrier(0)
; template <class Epi, class Sched, bool ALIGN_EPI = false, bool SP2 = false>
; __device__ __forceinline__ void gemm_phase(PG8_LAS unsigned char* lds, const Gemm g, const Sched& S, const Epi& E) {
;     ...
;         const bool has_next = S.next(ui + 1, nxt);
;         const char* nA = has_next ? (const char*)g.A + (size_t)nxt.pm * tstep : cA; const char* nB = has_next ? (const char*)g.Bt + (size_t)nxt.pn * tstep : cB;
;         for (int t = 0; t < nt; t += 2) {
;             const bool last = (t == nt - 2);
;             const char* a1 = cA + (size_t)(t + 1) * kstep;
;             const char* a2 = last ? nA : cA + (size_t)(t + 2) * kstep; const char* b2 = last ? nB : cB + (size_t)(t + 2) * kstep;
;             const char* a3 = a2 + kstep; const char* b3 = b2 + kstep;
;             if (last && has_next) S.a_ready(nxt);
;             if constexpr (SP2) {
;             PG8_LDB(B0, 0, 0); PG8_LDB(B1, 0, 1); PG8_SCHED; PG8_LDA(At, 0, 0); PG8_STAGE(PG8_SA(1, 1), a1 + hstep, voffA);
;             PG8_WAIT_V(8); PG8_WAIT_L(0); PG8_BAR; PG8_MMA(0, 0, At, B0); PG8_MMA(0, 1, At, B1); PG8_BAR; PG8_SCHED;
;             PG8_LDA(At, 0, 1); PG8_STAGE(PG8_SB(0, 0), b2, voffB); PG8_STAGE(PG8_SB(0, 1), b2 + hstep, voffB); PG8_STAGE(PG8_SA(0, 0), a2, voffA);
;             PG8_WAIT_V(8); PG8_WAIT_L(0); PG8_BAR; PG8_MMA(1, 0, At, B0); PG8_MMA(1, 1, At, B1); PG8_BAR; PG8_SCHED;
.LBB0_570:
	s_add_i32 s78, s20, 2
	s_add_u32 s79, s10, 0x80
	s_addc_u32 s21, s11, 0
	s_add_i32 s82, 0, 0x10000
	s_cmp_eq_u32 s68, s20
	s_cselect_b32 s21, s59, s21
	s_cselect_b32 s20, s58, s79
	s_cselect_b32 s81, s61, s63
	s_cselect_b32 s80, s60, s62
	s_add_i32 s79, 0, 0x14000
	ds_read_b128 v[82:85], v246
	ds_read_b128 v[98:101], v246 offset:1024
	ds_read_b128 v[102:105], v246 offset:2048
	ds_read_b128 v[106:109], v246 offset:3072
	ds_read_b128 v[146:149], v246 offset:16384
	ds_read_b128 v[150:153], v246 offset:17408
	ds_read_b128 v[154:157], v246 offset:18432
	ds_read_b128 v[158:161], v246 offset:19456
	v_lshl_add_u64 v[194:195], s[10:11], 0, v[224:225]
	s_add_i32 m0, s64, 0xc000
	ds_read_b128 v[162:165], v249
	ds_read_b128 v[166:169], v249 offset:1024
	ds_read_b128 v[170:173], v249 offset:2048
	ds_read_b128 v[174:177], v249 offset:3072
	ds_read_b128 v[178:181], v249 offset:4096
	ds_read_b128 v[182:185], v249 offset:5120
	ds_read_b128 v[186:189], v249 offset:6144
	ds_read_b128 v[190:193], v249 offset:7168
	global_load_lds_dwordx4 v[194:195], off
	s_add_i32 m0, s64, 0xe000
	v_lshl_add_u64 v[194:195], s[10:11], 0, v[226:227]
	global_load_lds_dwordx4 v[194:195], off
	s_waitcnt vmcnt(8)
	s_waitcnt lgkmcnt(0)
	s_barrier
	s_setprio 1
	s_waitcnt lgkmcnt(0)
	v_mfma_f32_16x16x32_bf16 v[142:145], v[82:85], v[162:165], v[142:145]
	v_mfma_f32_16x16x32_bf16 v[138:141], v[102:105], v[162:165], v[138:141]
	v_mfma_f32_16x16x32_bf16 v[126:129], v[82:85], v[170:173], v[126:129]
	v_mfma_f32_16x16x32_bf16 v[122:125], v[102:105], v[170:173], v[122:125]
	v_mfma_f32_16x16x32_bf16 v[110:113], v[82:85], v[178:181], v[110:113]
	v_mfma_f32_16x16x32_bf16 v[94:97], v[102:105], v[178:181], v[94:97]
	v_mfma_f32_16x16x32_bf16 v[78:81], v[82:85], v[186:189], v[78:81]
	v_mfma_f32_16x16x32_bf16 v[74:77], v[102:105], v[186:189], v[74:77]
	v_mfma_f32_16x16x32_bf16 v[142:145], v[98:101], v[166:169], v[142:145]
	v_mfma_f32_16x16x32_bf16 v[138:141], v[106:109], v[166:169], v[138:141]
	v_mfma_f32_16x16x32_bf16 v[126:129], v[98:101], v[174:177], v[126:129]
	v_mfma_f32_16x16x32_bf16 v[122:125], v[106:109], v[174:177], v[122:125]
	v_mfma_f32_16x16x32_bf16 v[110:113], v[98:101], v[182:185], v[110:113]
	v_mfma_f32_16x16x32_bf16 v[94:97], v[106:109], v[182:185], v[94:97]
	v_mfma_f32_16x16x32_bf16 v[78:81], v[98:101], v[190:193], v[78:81]
	v_mfma_f32_16x16x32_bf16 v[74:77], v[106:109], v[190:193], v[74:77]
	s_setprio 0
	s_setprio 1
	v_mfma_f32_16x16x32_bf16 v[134:137], v[146:149], v[162:165], v[134:137]
	v_mfma_f32_16x16x32_bf16 v[130:133], v[154:157], v[162:165], v[130:133]
	v_mfma_f32_16x16x32_bf16 v[118:121], v[146:149], v[170:173], v[118:121]
	v_mfma_f32_16x16x32_bf16 v[114:117], v[154:157], v[170:173], v[114:117]
	v_mfma_f32_16x16x32_bf16 v[90:93], v[146:149], v[178:181], v[90:93]
	v_mfma_f32_16x16x32_bf16 v[86:89], v[154:157], v[178:181], v[86:89]
	v_mfma_f32_16x16x32_bf16 v[70:73], v[146:149], v[186:189], v[70:73]
	v_mfma_f32_16x16x32_bf16 v[66:69], v[154:157], v[186:189], v[66:69]
	v_mfma_f32_16x16x32_bf16 v[134:137], v[150:153], v[166:169], v[134:137]
	v_mfma_f32_16x16x32_bf16 v[130:133], v[158:161], v[166:169], v[130:133]
	v_mfma_f32_16x16x32_bf16 v[118:121], v[150:153], v[174:177], v[118:121]
	v_mfma_f32_16x16x32_bf16 v[114:117], v[158:161], v[174:177], v[114:117]
	v_mfma_f32_16x16x32_bf16 v[90:93], v[150:153], v[182:185], v[90:93]
	v_mfma_f32_16x16x32_bf16 v[86:89], v[158:161], v[182:185], v[86:89]
	v_mfma_f32_16x16x32_bf16 v[70:73], v[150:153], v[190:193], v[70:73]
	v_mfma_f32_16x16x32_bf16 v[66:69], v[158:161], v[190:193], v[66:69]
	s_setprio 0
	s_barrier
	s_add_i32 s82, s82, s22
	v_lshl_add_u64 v[194:195], s[80:81], 0, v[0:1]
	s_mov_b32 m0, s82
	ds_read_b128 v[162:165], v249 offset:16384
	ds_read_b128 v[166:169], v249 offset:17408
	ds_read_b128 v[170:173], v249 offset:18432
	ds_read_b128 v[174:177], v249 offset:19456
	ds_read_b128 v[178:181], v249 offset:20480
	ds_read_b128 v[182:185], v249 offset:21504
	ds_read_b128 v[186:189], v249 offset:22528
	ds_read_b128 v[190:193], v249 offset:23552
	global_load_lds_dwordx4 v[194:195], off
	s_add_i32 m0, s82, 0x2000
	v_lshl_add_u64 v[196:197], s[80:81], 0, v[218:219]
	s_add_u32 s80, s80, s46
	s_addc_u32 s81, s81, s47
	s_add_i32 s79, s79, s22
	global_load_lds_dwordx4 v[196:197], off
	v_lshl_add_u64 v[198:199], s[80:81], 0, v[0:1]
	s_mov_b32 m0, s79
	v_lshl_add_u64 v[200:201], s[80:81], 0, v[218:219]
	global_load_lds_dwordx4 v[198:199], off
	s_add_i32 m0, s79, 0x2000
	v_lshl_add_u64 v[202:203], s[20:21], 0, v[0:1]
	global_load_lds_dwordx4 v[200:201], off
	s_mov_b32 m0, s64
	v_lshl_add_u64 v[204:205], s[20:21], 0, v[218:219]
	global_load_lds_dwordx4 v[202:203], off
	s_mov_b32 m0, s30
	s_nop 0
	global_load_lds_dwordx4 v[204:205], off
	s_waitcnt vmcnt(8)
	s_waitcnt lgkmcnt(0)
	s_barrier
; #define PG8_STAGE(bufoff, gbase, voff) do { _Pragma("unroll") for (int _i = 0; _i < 2; ++_i) \
;         __builtin_amdgcn_global_load_lds((const unsigned*)((const char*)(gbase) + (voff)[_i]), (PG8_LAS unsigned*)(lds + (bufoff) + ldsw + _i * 8192), 16, 0, 0); } while (0)
; #define PG8_LDA(dst, b, h) do { _Pragma("unroll") for (int m = 0; m < 4; ++m) _Pragma("unroll") for (int k = 0; k < 2; ++k) dst[m][k] = *(const PG8_LAS bf16x8*)(lds + PG8_SA(b, h) + aoff + m * 2048 + k * 1024); } while (0)
; #define PG8_LDB(dst, b, h) do { _Pragma("unroll") for (int n = 0; n < 2; ++n) _Pragma("unroll") for (int k = 0; k < 2; ++k) dst[n][k] = *(const PG8_LAS bf16x8*)(lds + PG8_SB(b, h) + boff + n * 2048 + k * 1024); } while (0)
; #define PG8_MMA(ai, bj, At, Bt) do { __builtin_amdgcn_s_setprio(1); _Pragma("unroll") for (int m = 0; m < 4; ++m) _Pragma("unroll") for (int n = 0; n < 2; ++n) _Pragma("unroll") for (int k = 0; k < 2; ++k) \
;         acc[ai][bj][m][n] = __builtin_amdgcn_mfma_f32_16x16x32_bf16(Bt[n][k], At[m][k], acc[ai][bj][m][n], 0, 0, 0); __builtin_amdgcn_s_setprio(0); } while (0)
; #define PG8_WAIT_V(n) asm volatile("s_waitcnt vmcnt(" #n ")" ::: "memory")
; #define PG8_WAIT_L(n) asm volatile("s_waitcnt lgkmcnt(" #n ")" ::: "memory")
; #define PG8_BAR __builtin_amdgcn_s_barrier()
; #define PG8_SCHED __builtin_amdgcn_sched_barrier(0)
; template <class Epi, class Sched, bool ALIGN_EPI = false, bool SP2 = false>
; __device__ __forceinline__ void gemm_phase(PG8_LAS unsigned char* lds, const Gemm g, const Sched& S, const Epi& E) {
;     ...
;             PG8_WAIT_V(8); PG8_WAIT_L(0); PG8_BAR; PG8_MMA(1, 0, At, B0); PG8_MMA(1, 1, At, B1); PG8_BAR; PG8_SCHED;
;             PG8_LDB(B0, 1, 0); PG8_LDB(B1, 1, 1); PG8_SCHED; PG8_LDA(At, 1, 0); PG8_STAGE(PG8_SA(0, 1), a2 + hstep, voffA);
;             PG8_WAIT_V(8); PG8_WAIT_L(0); PG8_BAR; PG8_MMA(0, 0, At, B0); PG8_MMA(0, 1, At, B1); PG8_BAR; PG8_SCHED;
	s_setprio 1
	s_waitcnt lgkmcnt(0)
	v_mfma_f32_16x16x32_bf16 v[62:65], v[82:85], v[162:165], v[62:65]
	v_mfma_f32_16x16x32_bf16 v[58:61], v[102:105], v[162:165], v[58:61]
	v_mfma_f32_16x16x32_bf16 v[46:49], v[82:85], v[170:173], v[46:49]
	v_mfma_f32_16x16x32_bf16 v[42:45], v[102:105], v[170:173], v[42:45]
	v_mfma_f32_16x16x32_bf16 v[30:33], v[82:85], v[178:181], v[30:33]
	v_mfma_f32_16x16x32_bf16 v[26:29], v[102:105], v[178:181], v[26:29]
	v_mfma_f32_16x16x32_bf16 v[14:17], v[82:85], v[186:189], v[14:17]
	v_mfma_f32_16x16x32_bf16 v[10:13], v[102:105], v[186:189], v[10:13]
	v_mfma_f32_16x16x32_bf16 v[62:65], v[98:101], v[166:169], v[62:65]
	v_mfma_f32_16x16x32_bf16 v[58:61], v[106:109], v[166:169], v[58:61]
	v_mfma_f32_16x16x32_bf16 v[46:49], v[98:101], v[174:177], v[46:49]
	v_mfma_f32_16x16x32_bf16 v[42:45], v[106:109], v[174:177], v[42:45]
	v_mfma_f32_16x16x32_bf16 v[30:33], v[98:101], v[182:185], v[30:33]
	v_mfma_f32_16x16x32_bf16 v[26:29], v[106:109], v[182:185], v[26:29]
	v_mfma_f32_16x16x32_bf16 v[14:17], v[98:101], v[190:193], v[14:17]
	v_mfma_f32_16x16x32_bf16 v[10:13], v[106:109], v[190:193], v[10:13]
	s_setprio 0
	s_setprio 1
	v_mfma_f32_16x16x32_bf16 v[54:57], v[146:149], v[162:165], v[54:57]
	v_mfma_f32_16x16x32_bf16 v[50:53], v[154:157], v[162:165], v[50:53]
	v_mfma_f32_16x16x32_bf16 v[38:41], v[146:149], v[170:173], v[38:41]
	v_mfma_f32_16x16x32_bf16 v[34:37], v[154:157], v[170:173], v[34:37]
	v_mfma_f32_16x16x32_bf16 v[22:25], v[146:149], v[178:181], v[22:25]
	v_mfma_f32_16x16x32_bf16 v[18:21], v[154:157], v[178:181], v[18:21]
	v_mfma_f32_16x16x32_bf16 v[6:9], v[146:149], v[186:189], v[6:9]
	v_mfma_f32_16x16x32_bf16 v[2:5], v[154:157], v[186:189], v[2:5]
	v_mfma_f32_16x16x32_bf16 v[54:57], v[150:153], v[166:169], v[54:57]
	v_mfma_f32_16x16x32_bf16 v[50:53], v[158:161], v[166:169], v[50:53]
	v_mfma_f32_16x16x32_bf16 v[38:41], v[150:153], v[174:177], v[38:41]
	v_mfma_f32_16x16x32_bf16 v[34:37], v[158:161], v[174:177], v[34:37]
	v_mfma_f32_16x16x32_bf16 v[22:25], v[150:153], v[182:185], v[22:25]
	v_mfma_f32_16x16x32_bf16 v[18:21], v[158:161], v[182:185], v[18:21]
	v_mfma_f32_16x16x32_bf16 v[6:9], v[150:153], v[190:193], v[6:9]
	v_mfma_f32_16x16x32_bf16 v[2:5], v[158:161], v[190:193], v[2:5]
	s_setprio 0
	s_barrier
	s_add_i32 s79, 0, 0x18000
	s_add_i32 s80, 0, 0x1c000
	ds_read_b128 v[82:85], v246 offset:32768
	ds_read_b128 v[98:101], v246 offset:33792
	ds_read_b128 v[102:105], v246 offset:34816
	ds_read_b128 v[106:109], v246 offset:35840
	ds_read_b128 v[146:149], v246 offset:49152
	ds_read_b128 v[150:153], v246 offset:50176
	ds_read_b128 v[154:157], v246 offset:51200
	ds_read_b128 v[158:161], v246 offset:52224
	s_add_u32 s20, s20, s46
	s_addc_u32 s21, s21, s47
	s_mov_b32 m0, s31
	v_lshl_add_u64 v[206:207], s[20:21], 0, v[0:1]
	ds_read_b128 v[162:165], v249 offset:32768
	ds_read_b128 v[166:169], v249 offset:33792
	ds_read_b128 v[170:173], v249 offset:34816
	ds_read_b128 v[174:177], v249 offset:35840
	ds_read_b128 v[178:181], v249 offset:36864
	ds_read_b128 v[182:185], v249 offset:37888
	ds_read_b128 v[186:189], v249 offset:38912
	ds_read_b128 v[190:193], v249 offset:39936
	global_load_lds_dwordx4 v[206:207], off
	s_mov_b32 m0, s33
	v_lshl_add_u64 v[206:207], s[20:21], 0, v[218:219]
	global_load_lds_dwordx4 v[206:207], off
	s_waitcnt vmcnt(8)
	s_waitcnt lgkmcnt(0)
	s_barrier
	s_setprio 1
	s_waitcnt lgkmcnt(0)
	v_mfma_f32_16x16x32_bf16 v[142:145], v[82:85], v[162:165], v[142:145]
	v_mfma_f32_16x16x32_bf16 v[138:141], v[102:105], v[162:165], v[138:141]
	v_mfma_f32_16x16x32_bf16 v[126:129], v[82:85], v[170:173], v[126:129]
	v_mfma_f32_16x16x32_bf16 v[122:125], v[102:105], v[170:173], v[122:125]
	v_mfma_f32_16x16x32_bf16 v[110:113], v[82:85], v[178:181], v[110:113]
	v_mfma_f32_16x16x32_bf16 v[94:97], v[102:105], v[178:181], v[94:97]
	v_mfma_f32_16x16x32_bf16 v[78:81], v[82:85], v[186:189], v[78:81]
	v_mfma_f32_16x16x32_bf16 v[74:77], v[102:105], v[186:189], v[74:77]
	v_mfma_f32_16x16x32_bf16 v[142:145], v[98:101], v[166:169], v[142:145]
	v_mfma_f32_16x16x32_bf16 v[138:141], v[106:109], v[166:169], v[138:141]
	v_mfma_f32_16x16x32_bf16 v[126:129], v[98:101], v[174:177], v[126:129]
	v_mfma_f32_16x16x32_bf16 v[122:125], v[106:109], v[174:177], v[122:125]
	v_mfma_f32_16x16x32_bf16 v[110:113], v[98:101], v[182:185], v[110:113]
	v_mfma_f32_16x16x32_bf16 v[94:97], v[106:109], v[182:185], v[94:97]
	v_mfma_f32_16x16x32_bf16 v[78:81], v[98:101], v[190:193], v[78:81]
	v_mfma_f32_16x16x32_bf16 v[74:77], v[106:109], v[190:193], v[74:77]
	s_setprio 0
	s_setprio 1
	v_mfma_f32_16x16x32_bf16 v[134:137], v[146:149], v[162:165], v[134:137]
	v_mfma_f32_16x16x32_bf16 v[130:133], v[154:157], v[162:165], v[130:133]
	v_mfma_f32_16x16x32_bf16 v[118:121], v[146:149], v[170:173], v[118:121]
	v_mfma_f32_16x16x32_bf16 v[114:117], v[154:157], v[170:173], v[114:117]
	v_mfma_f32_16x16x32_bf16 v[90:93], v[146:149], v[178:181], v[90:93]
	v_mfma_f32_16x16x32_bf16 v[86:89], v[154:157], v[178:181], v[86:89]
	v_mfma_f32_16x16x32_bf16 v[70:73], v[146:149], v[186:189], v[70:73]
	v_mfma_f32_16x16x32_bf16 v[66:69], v[154:157], v[186:189], v[66:69]
	v_mfma_f32_16x16x32_bf16 v[134:137], v[150:153], v[166:169], v[134:137]
	v_mfma_f32_16x16x32_bf16 v[130:133], v[158:161], v[166:169], v[130:133]
	v_mfma_f32_16x16x32_bf16 v[118:121], v[150:153], v[174:177], v[118:121]
	v_mfma_f32_16x16x32_bf16 v[114:117], v[158:161], v[174:177], v[114:117]
	v_mfma_f32_16x16x32_bf16 v[90:93], v[150:153], v[182:185], v[90:93]
	v_mfma_f32_16x16x32_bf16 v[86:89], v[158:161], v[182:185], v[86:89]
	v_mfma_f32_16x16x32_bf16 v[70:73], v[150:153], v[190:193], v[70:73]
	v_mfma_f32_16x16x32_bf16 v[66:69], v[158:161], v[190:193], v[66:69]
	s_setprio 0
	s_barrier
; #define PG8_STAGE(bufoff, gbase, voff) do { _Pragma("unroll") for (int _i = 0; _i < 2; ++_i) \
;         __builtin_amdgcn_global_load_lds((const unsigned*)((const char*)(gbase) + (voff)[_i]), (PG8_LAS unsigned*)(lds + (bufoff) + ldsw + _i * 8192), 16, 0, 0); } while (0)
; #define PG8_LDA(dst, b, h) do { _Pragma("unroll") for (int m = 0; m < 4; ++m) _Pragma("unroll") for (int k = 0; k < 2; ++k) dst[m][k] = *(const PG8_LAS bf16x8*)(lds + PG8_SA(b, h) + aoff + m * 2048 + k * 1024); } while (0)
; #define PG8_MMA(ai, bj, At, Bt) do { __builtin_amdgcn_s_setprio(1); _Pragma("unroll") for (int m = 0; m < 4; ++m) _Pragma("unroll") for (int n = 0; n < 2; ++n) _Pragma("unroll") for (int k = 0; k < 2; ++k) \
;         acc[ai][bj][m][n] = __builtin_amdgcn_mfma_f32_16x16x32_bf16(Bt[n][k], At[m][k], acc[ai][bj][m][n], 0, 0, 0); __builtin_amdgcn_s_setprio(0); } while (0)
; #define PG8_WAIT_V(n) asm volatile("s_waitcnt vmcnt(" #n ")" ::: "memory")
; #define PG8_WAIT_L(n) asm volatile("s_waitcnt lgkmcnt(" #n ")" ::: "memory")
; #define PG8_BAR __builtin_amdgcn_s_barrier()
; #define PG8_SCHED __builtin_amdgcn_sched_barrier(0)
; template <class Epi, class Sched, bool ALIGN_EPI = false, bool SP2 = false>
; __device__ __forceinline__ void gemm_phase(PG8_LAS unsigned char* lds, const Gemm g, const Sched& S, const Epi& E) {
;     ...
;         for (int t = 0; t < nt; t += 2) {
;     ...
;             PG8_LDA(At, 1, 1); PG8_STAGE(PG8_SB(1, 0), b3, voffB); PG8_STAGE(PG8_SB(1, 1), b3 + hstep, voffB); PG8_STAGE(PG8_SA(1, 0), a3, voffA);
;             PG8_WAIT_V(8); PG8_WAIT_L(0); PG8_BAR; PG8_MMA(1, 0, At, B0); PG8_MMA(1, 1, At, B1); PG8_BAR; PG8_SCHED;
	s_add_i32 s20, s79, s22
	v_lshl_add_u64 v[194:195], v[194:195], 0, s[24:25]
	s_mov_b32 m0, s20
	ds_read_b128 v[162:165], v249 offset:49152
	ds_read_b128 v[166:169], v249 offset:50176
	ds_read_b128 v[170:173], v249 offset:51200
	ds_read_b128 v[174:177], v249 offset:52224
	ds_read_b128 v[178:181], v249 offset:53248
	ds_read_b128 v[182:185], v249 offset:54272
	ds_read_b128 v[186:189], v249 offset:55296
	ds_read_b128 v[190:193], v249 offset:56320
	global_load_lds_dwordx4 v[194:195], off
	v_lshl_add_u64 v[194:195], v[196:197], 0, s[24:25]
	s_add_i32 m0, s20, 0x2000
	s_add_i32 s20, s80, s22
	global_load_lds_dwordx4 v[194:195], off
	s_mov_b32 m0, s20
	v_lshl_add_u64 v[194:195], v[198:199], 0, s[24:25]
	global_load_lds_dwordx4 v[194:195], off
	s_add_i32 m0, s20, 0x2000
	v_lshl_add_u64 v[194:195], v[200:201], 0, s[24:25]
	global_load_lds_dwordx4 v[194:195], off
	s_mov_b32 m0, s39
	v_lshl_add_u64 v[194:195], v[202:203], 0, s[24:25]
	global_load_lds_dwordx4 v[194:195], off
	s_mov_b32 m0, s65
	v_lshl_add_u64 v[194:195], v[204:205], 0, s[24:25]
	global_load_lds_dwordx4 v[194:195], off
	s_waitcnt vmcnt(8)
	s_waitcnt lgkmcnt(0)
	s_barrier
	s_setprio 1
	s_waitcnt lgkmcnt(0)
	v_mfma_f32_16x16x32_bf16 v[62:65], v[82:85], v[162:165], v[62:65]
	v_mfma_f32_16x16x32_bf16 v[58:61], v[102:105], v[162:165], v[58:61]
	v_mfma_f32_16x16x32_bf16 v[46:49], v[82:85], v[170:173], v[46:49]
	v_mfma_f32_16x16x32_bf16 v[42:45], v[102:105], v[170:173], v[42:45]
	v_mfma_f32_16x16x32_bf16 v[30:33], v[82:85], v[178:181], v[30:33]
	v_mfma_f32_16x16x32_bf16 v[26:29], v[102:105], v[178:181], v[26:29]
	v_mfma_f32_16x16x32_bf16 v[14:17], v[82:85], v[186:189], v[14:17]
	v_mfma_f32_16x16x32_bf16 v[10:13], v[102:105], v[186:189], v[10:13]
	v_mfma_f32_16x16x32_bf16 v[62:65], v[98:101], v[166:169], v[62:65]
	v_mfma_f32_16x16x32_bf16 v[58:61], v[106:109], v[166:169], v[58:61]
	v_mfma_f32_16x16x32_bf16 v[46:49], v[98:101], v[174:177], v[46:49]
	v_mfma_f32_16x16x32_bf16 v[42:45], v[106:109], v[174:177], v[42:45]
	v_mfma_f32_16x16x32_bf16 v[30:33], v[98:101], v[182:185], v[30:33]
	v_mfma_f32_16x16x32_bf16 v[26:29], v[106:109], v[182:185], v[26:29]
	v_mfma_f32_16x16x32_bf16 v[14:17], v[98:101], v[190:193], v[14:17]
	v_mfma_f32_16x16x32_bf16 v[10:13], v[106:109], v[190:193], v[10:13]
	s_setprio 0
	s_setprio 1
	v_mfma_f32_16x16x32_bf16 v[54:57], v[146:149], v[162:165], v[54:57]
	v_mfma_f32_16x16x32_bf16 v[50:53], v[154:157], v[162:165], v[50:53]
	v_mfma_f32_16x16x32_bf16 v[38:41], v[146:149], v[170:173], v[38:41]
	v_mfma_f32_16x16x32_bf16 v[34:37], v[154:157], v[170:173], v[34:37]
	v_mfma_f32_16x16x32_bf16 v[22:25], v[146:149], v[178:181], v[22:25]
	v_mfma_f32_16x16x32_bf16 v[18:21], v[154:157], v[178:181], v[18:21]
	v_mfma_f32_16x16x32_bf16 v[6:9], v[146:149], v[186:189], v[6:9]
	v_mfma_f32_16x16x32_bf16 v[2:5], v[154:157], v[186:189], v[2:5]
	v_mfma_f32_16x16x32_bf16 v[54:57], v[150:153], v[166:169], v[54:57]
	v_mfma_f32_16x16x32_bf16 v[50:53], v[158:161], v[166:169], v[50:53]
	v_mfma_f32_16x16x32_bf16 v[38:41], v[150:153], v[174:177], v[38:41]
	v_mfma_f32_16x16x32_bf16 v[34:37], v[158:161], v[174:177], v[34:37]
	v_mfma_f32_16x16x32_bf16 v[22:25], v[150:153], v[182:185], v[22:25]
	v_mfma_f32_16x16x32_bf16 v[18:21], v[158:161], v[182:185], v[18:21]
	v_mfma_f32_16x16x32_bf16 v[6:9], v[150:153], v[190:193], v[6:9]
	v_mfma_f32_16x16x32_bf16 v[2:5], v[158:161], v[190:193], v[2:5]
	s_setprio 0
	s_barrier
	s_add_u32 s10, s10, 0x100
	s_addc_u32 s11, s11, 0
	s_add_u32 s62, s62, 0x100
	s_addc_u32 s63, s63, 0
	s_cmp_ge_i32 s78, s67
	s_mov_b32 s20, s78
	s_cbranch_scc0 .LBB0_570

; #define PG8_STAGE(bufoff, gbase, voff) do { _Pragma("unroll") for (int _i = 0; _i < 2; ++_i) \
;         __builtin_amdgcn_global_load_lds((const unsigned*)((const char*)(gbase) + (voff)[_i]), (PG8_LAS unsigned*)(lds + (bufoff) + ldsw + _i * 8192), 16, 0, 0); } while (0)
; #define PG8_WAIT_V(n) asm volatile("s_waitcnt vmcnt(" #n ")" ::: "memory")
; #define PG8_BAR __builtin_amdgcn_s_barrier()
; template <class Epi, class Sched, bool ALIGN_EPI = false, bool SP2 = false>
; __device__ __forceinline__ void gemm_phase(PG8_LAS unsigned char* lds, const Gemm g, const Sched& S, const Epi& E) {
;     ...
;     for (int i = 0; i < 2; ++i) { int R, C; stage_rc(tid * 16 + i * 8192, R, C); const int Rb = Epi::PERM ? ((R & ~31) + perm32(R & 31)) : R;
;         voffA[i] = (unsigned)(R * K + C) * 2u; voffB[i] = (unsigned)(Rb * K + C) * 2u; }
;     const size_t kstep = (size_t)(BK * 2);
;     const size_t hstep = (size_t)HALF * K * 2;
;     const size_t tstep = 2 * hstep;
;     const unsigned ldsw = (unsigned)wid * 1024u;
;     const int aoff = lds_byte(wr * 64 + fr, fq * 8), boff = lds_byte(wc * 32 + fr, fq * 8);
;     ...
;         PG8_STAGE(PG8_SB(1, 0), cB + kstep, voffB); PG8_STAGE(PG8_SA(1, 0), cA + kstep, voffA); PG8_STAGE(PG8_SB(1, 1), cB + hstep + kstep, voffB);
;         PG8_WAIT_V(6); PG8_BAR;
.LBB0_630:
	s_cmp_lg_u32 s73, 1
	s_cselect_b64 s[42:43], -1, 0
	s_cmp_eq_u32 s73, 1
	s_cselect_b32 s49, 0, s89
	s_cselect_b32 s48, 0, s88
	s_add_i32 m0, s55, 0x18000
	v_lshl_add_u64 v[10:11], v[10:11], 0, s[24:25]
	s_waitcnt vmcnt(2)
	s_barrier
	global_load_lds_dwordx4 v[10:11], off
	v_lshl_add_u64 v[6:7], v[6:7], 0, s[24:25]
	s_add_i32 m0, s55, 0x1a000
	s_add_i32 s59, s55, 0x8000
	global_load_lds_dwordx4 v[6:7], off
	v_lshl_add_u64 v[6:7], v[8:9], 0, s[24:25]
	s_mov_b32 m0, s59
	s_add_i32 s60, s55, 0xa000
	global_load_lds_dwordx4 v[6:7], off
	v_lshl_add_u64 v[6:7], v[12:13], 0, s[24:25]
	s_mov_b32 m0, s60
	v_lshl_add_u64 v[4:5], v[4:5], 0, s[24:25]
	global_load_lds_dwordx4 v[6:7], off
	s_add_i32 m0, s55, 0x1c000
	v_lshl_add_u64 v[2:3], v[2:3], 0, s[24:25]
	global_load_lds_dwordx4 v[4:5], off
	s_add_i32 m0, s55, 0x1e000
	v_bfe_u32 v4, v14, 4, 2
	global_load_lds_dwordx4 v[2:3], off
	s_lshr_b32 s7, s7, 26
	v_and_b32_e32 v3, 15, v14
	s_add_i32 s7, s6, s7
	v_lshlrev_b32_e32 v2, 4, v4
	v_lshlrev_b32_e32 v5, 2, v14
	s_ashr_i32 s62, s7, 6
	v_lshl_or_b32 v180, s9, 6, v3
	v_lshl_or_b32 v3, v3, 6, v2
	s_lshl_b32 s7, s9, 13
	v_and_b32_e32 v5, 32, v5
	v_bitop3_b32 v6, v3, s7, v5 bitop3:0xde
	s_lshl_b32 s7, s8, 5
	s_and_b32 s7, s7, 0x60
	s_lshl_b32 s8, s7, 7
	v_bitop3_b32 v181, v3, s8, v5 bitop3:0xde
	v_add_u32_e32 v181, 0x10000, v181
	v_mov_b32_e32 v3, v1
	v_lshl_add_u64 v[160:161], s[48:49], 0, v[2:3]
	v_add_u32_e32 v2, v20, v18
	s_cmp_gt_i32 s6, 63
	v_add_lshl_u32 v2, v2, v19, 1
	s_waitcnt vmcnt(6)
	s_cselect_b64 s[44:45], -1, 0
	s_add_i32 s63, s62, -2
	v_lshl_add_u64 v[162:163], s[10:11], 0, v[2:3]
	v_add_u32_e32 v2, v17, v15
	s_cmpk_lt_u32 s5, 0x100
	v_add_lshl_u32 v2, v2, v16, 1
	s_mov_b32 s61, 0
	s_cselect_b64 s[46:47], -1, 0
	s_ashr_i32 s5, s4, 31
	v_lshl_or_b32 v182, v4, 3, s7
	v_lshl_add_u64 v[164:165], s[10:11], 0, v[2:3]
	v_add_u32_e32 v183, 0, v6
	s_barrier
	s_branch .LBB0_633

; #define PG8_STAGE(bufoff, gbase, voff) do { _Pragma("unroll") for (int _i = 0; _i < 2; ++_i) \
;         __builtin_amdgcn_global_load_lds((const unsigned*)((const char*)(gbase) + (voff)[_i]), (PG8_LAS unsigned*)(lds + (bufoff) + ldsw + _i * 8192), 16, 0, 0); } while (0)
; #define PG8_LDA(dst, b, h) do { _Pragma("unroll") for (int m = 0; m < 4; ++m) _Pragma("unroll") for (int k = 0; k < 2; ++k) dst[m][k] = *(const PG8_LAS bf16x8*)(lds + PG8_SA(b, h) + aoff + m * 2048 + k * 1024); } while (0)
; #define PG8_LDB(dst, b, h) do { _Pragma("unroll") for (int n = 0; n < 2; ++n) _Pragma("unroll") for (int k = 0; k < 2; ++k) dst[n][k] = *(const PG8_LAS bf16x8*)(lds + PG8_SB(b, h) + boff + n * 2048 + k * 1024); } while (0)
; #define PG8_WAIT_V(n) asm volatile("s_waitcnt vmcnt(" #n ")" ::: "memory")
; #define PG8_WAIT_L(n) asm volatile("s_waitcnt lgkmcnt(" #n ")" ::: "memory")
; #define PG8_BAR __builtin_amdgcn_s_barrier()
; #define PG8_SCHED __builtin_amdgcn_sched_barrier(0)
; template <class Epi, class Sched, bool ALIGN_EPI = false, bool SP2 = false>
; __device__ __forceinline__ void gemm_phase(PG8_LAS unsigned char* lds, const Gemm g, const Sched& S, const Epi& E) {
;     ...
;         const bool has_next = S.next(ui + 1, nxt);
;         const char* nA = has_next ? (const char*)g.A + (size_t)nxt.pm * tstep : cA; const char* nB = has_next ? (const char*)g.Bt + (size_t)nxt.pn * tstep : cB;
;         for (int t = 0; t < nt; t += 2) {
;             const bool last = (t == nt - 2);
;             const char* a1 = cA + (size_t)(t + 1) * kstep;
;             const char* a2 = last ? nA : cA + (size_t)(t + 2) * kstep; const char* b2 = last ? nB : cB + (size_t)(t + 2) * kstep;
;             const char* a3 = a2 + kstep; const char* b3 = b2 + kstep;
;             if (last && has_next) S.a_ready(nxt);
;             if constexpr (SP2) {
;             PG8_LDB(B0, 0, 0); PG8_LDB(B1, 0, 1); PG8_SCHED; PG8_LDA(At, 0, 0); PG8_STAGE(PG8_SA(1, 1), a1 + hstep, voffA);
;             PG8_WAIT_V(8); PG8_WAIT_L(0); PG8_BAR; PG8_MMA(0, 0, At, B0); PG8_MMA(0, 1, At, B1); PG8_BAR; PG8_SCHED;
;             PG8_LDA(At, 0, 1); PG8_STAGE(PG8_SB(0, 0), b2, voffB); PG8_STAGE(PG8_SB(0, 1), b2 + hstep, voffB); PG8_STAGE(PG8_SA(0, 0), a2, voffA);
;             PG8_WAIT_V(8); PG8_WAIT_L(0); PG8_BAR; PG8_MMA(1, 0, At, B0); PG8_MMA(1, 1, At, B1); PG8_BAR; PG8_SCHED;
.LBB0_641:
	s_add_i32 s68, s20, 2
	s_add_u32 s69, s8, 0x80
	s_addc_u32 s21, s9, 0
	s_add_i32 s72, 0, 0x10000
	s_cmp_eq_u32 s63, s20
	s_cselect_b32 s21, s49, s21
	s_cselect_b32 s20, s48, s69
	s_cselect_b32 s71, s51, s53
	s_cselect_b32 s70, s50, s52
	s_add_i32 s69, 0, 0x14000
	ds_read_b128 v[130:133], v181
	ds_read_b128 v[134:137], v181 offset:1024
	ds_read_b128 v[138:141], v181 offset:2048
	ds_read_b128 v[142:145], v181 offset:3072
	ds_read_b128 v[146:149], v181 offset:16384
	ds_read_b128 v[150:153], v181 offset:17408
	ds_read_b128 v[166:169], v181 offset:18432
	ds_read_b128 v[170:173], v181 offset:19456
	v_lshl_add_u64 v[178:179], s[8:9], 0, v[162:163]
	s_add_i32 m0, s55, 0xc000
	ds_read_b128 v[174:177], v183
	ds_read_b128 v[184:187], v183 offset:1024
	ds_read_b128 v[188:191], v183 offset:2048
	ds_read_b128 v[192:195], v183 offset:3072
	ds_read_b128 v[196:199], v183 offset:4096
	ds_read_b128 v[200:203], v183 offset:5120
	ds_read_b128 v[204:207], v183 offset:6144
	ds_read_b128 v[208:211], v183 offset:7168
	global_load_lds_dwordx4 v[178:179], off
	s_add_i32 m0, s55, 0xe000
	v_lshl_add_u64 v[178:179], s[8:9], 0, v[164:165]
	global_load_lds_dwordx4 v[178:179], off
	s_waitcnt vmcnt(8)
	s_waitcnt lgkmcnt(0)
	s_barrier
	s_setprio 1
	s_waitcnt lgkmcnt(0)
	v_mfma_f32_16x16x32_bf16 v[122:125], v[130:133], v[174:177], v[122:125]
	v_mfma_f32_16x16x32_bf16 v[118:121], v[138:141], v[174:177], v[118:121]
	v_mfma_f32_16x16x32_bf16 v[106:109], v[130:133], v[188:191], v[106:109]
	v_mfma_f32_16x16x32_bf16 v[102:105], v[138:141], v[188:191], v[102:105]
	v_mfma_f32_16x16x32_bf16 v[90:93], v[130:133], v[196:199], v[90:93]
	v_mfma_f32_16x16x32_bf16 v[86:89], v[138:141], v[196:199], v[86:89]
	v_mfma_f32_16x16x32_bf16 v[74:77], v[130:133], v[204:207], v[74:77]
	v_mfma_f32_16x16x32_bf16 v[70:73], v[138:141], v[204:207], v[70:73]
	v_mfma_f32_16x16x32_bf16 v[122:125], v[134:137], v[184:187], v[122:125]
	v_mfma_f32_16x16x32_bf16 v[118:121], v[142:145], v[184:187], v[118:121]
	v_mfma_f32_16x16x32_bf16 v[106:109], v[134:137], v[192:195], v[106:109]
	v_mfma_f32_16x16x32_bf16 v[102:105], v[142:145], v[192:195], v[102:105]
	v_mfma_f32_16x16x32_bf16 v[90:93], v[134:137], v[200:203], v[90:93]
	v_mfma_f32_16x16x32_bf16 v[86:89], v[142:145], v[200:203], v[86:89]
	v_mfma_f32_16x16x32_bf16 v[74:77], v[134:137], v[208:211], v[74:77]
	v_mfma_f32_16x16x32_bf16 v[70:73], v[142:145], v[208:211], v[70:73]
	s_setprio 0
	s_setprio 1
	v_mfma_f32_16x16x32_bf16 v[126:129], v[146:149], v[174:177], v[126:129]
	v_mfma_f32_16x16x32_bf16 v[114:117], v[166:169], v[174:177], v[114:117]
	v_mfma_f32_16x16x32_bf16 v[110:113], v[146:149], v[188:191], v[110:113]
	v_mfma_f32_16x16x32_bf16 v[98:101], v[166:169], v[188:191], v[98:101]
	v_mfma_f32_16x16x32_bf16 v[94:97], v[146:149], v[196:199], v[94:97]
	v_mfma_f32_16x16x32_bf16 v[82:85], v[166:169], v[196:199], v[82:85]
	v_mfma_f32_16x16x32_bf16 v[78:81], v[146:149], v[204:207], v[78:81]
	v_mfma_f32_16x16x32_bf16 v[66:69], v[166:169], v[204:207], v[66:69]
	v_mfma_f32_16x16x32_bf16 v[126:129], v[150:153], v[184:187], v[126:129]
	v_mfma_f32_16x16x32_bf16 v[114:117], v[170:173], v[184:187], v[114:117]
	v_mfma_f32_16x16x32_bf16 v[110:113], v[150:153], v[192:195], v[110:113]
	v_mfma_f32_16x16x32_bf16 v[98:101], v[170:173], v[192:195], v[98:101]
	v_mfma_f32_16x16x32_bf16 v[94:97], v[150:153], v[200:203], v[94:97]
	v_mfma_f32_16x16x32_bf16 v[82:85], v[170:173], v[200:203], v[82:85]
	v_mfma_f32_16x16x32_bf16 v[78:81], v[150:153], v[208:211], v[78:81]
	v_mfma_f32_16x16x32_bf16 v[66:69], v[170:173], v[208:211], v[66:69]
	s_setprio 0
	s_barrier
	s_add_i32 s72, s72, s23
	v_lshl_add_u64 v[178:179], s[70:71], 0, v[0:1]
	s_mov_b32 m0, s72
	ds_read_b128 v[174:177], v183 offset:16384
	ds_read_b128 v[184:187], v183 offset:17408
	ds_read_b128 v[188:191], v183 offset:18432
	ds_read_b128 v[192:195], v183 offset:19456
	ds_read_b128 v[196:199], v183 offset:20480
	ds_read_b128 v[200:203], v183 offset:21504
	ds_read_b128 v[204:207], v183 offset:22528
	ds_read_b128 v[208:211], v183 offset:23552
	global_load_lds_dwordx4 v[178:179], off
	s_add_i32 m0, s72, 0x2000
	v_lshl_add_u64 v[212:213], s[70:71], 0, v[154:155]
	s_add_u32 s70, s70, s10
	s_addc_u32 s71, s71, s11
	s_add_i32 s69, s69, s23
	global_load_lds_dwordx4 v[212:213], off
	v_lshl_add_u64 v[214:215], s[70:71], 0, v[0:1]
	s_mov_b32 m0, s69
	v_lshl_add_u64 v[218:219], s[70:71], 0, v[154:155]
	global_load_lds_dwordx4 v[214:215], off
	s_add_i32 m0, s69, 0x2000
	v_lshl_add_u64 v[220:221], s[20:21], 0, v[158:159]
	global_load_lds_dwordx4 v[218:219], off
	s_mov_b32 m0, s55
	v_lshl_add_u64 v[222:223], s[20:21], 0, v[156:157]
	global_load_lds_dwordx4 v[220:221], off
	s_mov_b32 m0, s56
	s_nop 0
	global_load_lds_dwordx4 v[222:223], off
	s_waitcnt vmcnt(8)
	s_waitcnt lgkmcnt(0)
	s_barrier
; #define PG8_STAGE(bufoff, gbase, voff) do { _Pragma("unroll") for (int _i = 0; _i < 2; ++_i) \
;         __builtin_amdgcn_global_load_lds((const unsigned*)((const char*)(gbase) + (voff)[_i]), (PG8_LAS unsigned*)(lds + (bufoff) + ldsw + _i * 8192), 16, 0, 0); } while (0)
; #define PG8_LDA(dst, b, h) do { _Pragma("unroll") for (int m = 0; m < 4; ++m) _Pragma("unroll") for (int k = 0; k < 2; ++k) dst[m][k] = *(const PG8_LAS bf16x8*)(lds + PG8_SA(b, h) + aoff + m * 2048 + k * 1024); } while (0)
; #define PG8_LDB(dst, b, h) do { _Pragma("unroll") for (int n = 0; n < 2; ++n) _Pragma("unroll") for (int k = 0; k < 2; ++k) dst[n][k] = *(const PG8_LAS bf16x8*)(lds + PG8_SB(b, h) + boff + n * 2048 + k * 1024); } while (0)
; #define PG8_MMA(ai, bj, At, Bt) do { __builtin_amdgcn_s_setprio(1); _Pragma("unroll") for (int m = 0; m < 4; ++m) _Pragma("unroll") for (int n = 0; n < 2; ++n) _Pragma("unroll") for (int k = 0; k < 2; ++k) \
;         acc[ai][bj][m][n] = __builtin_amdgcn_mfma_f32_16x16x32_bf16(Bt[n][k], At[m][k], acc[ai][bj][m][n], 0, 0, 0); __builtin_amdgcn_s_setprio(0); } while (0)
; #define PG8_WAIT_V(n) asm volatile("s_waitcnt vmcnt(" #n ")" ::: "memory")
; #define PG8_WAIT_L(n) asm volatile("s_waitcnt lgkmcnt(" #n ")" ::: "memory")
; #define PG8_BAR __builtin_amdgcn_s_barrier()
; #define PG8_SCHED __builtin_amdgcn_sched_barrier(0)
; template <class Epi, class Sched, bool ALIGN_EPI = false, bool SP2 = false>
; __device__ __forceinline__ void gemm_phase(PG8_LAS unsigned char* lds, const Gemm g, const Sched& S, const Epi& E) {
;     ...
;             PG8_WAIT_V(8); PG8_WAIT_L(0); PG8_BAR; PG8_MMA(1, 0, At, B0); PG8_MMA(1, 1, At, B1); PG8_BAR; PG8_SCHED;
;             PG8_LDB(B0, 1, 0); PG8_LDB(B1, 1, 1); PG8_SCHED; PG8_LDA(At, 1, 0); PG8_STAGE(PG8_SA(0, 1), a2 + hstep, voffA);
;             PG8_WAIT_V(8); PG8_WAIT_L(0); PG8_BAR; PG8_MMA(0, 0, At, B0); PG8_MMA(0, 1, At, B1); PG8_BAR; PG8_SCHED;
	s_setprio 1
	s_waitcnt lgkmcnt(0)
	v_mfma_f32_16x16x32_bf16 v[58:61], v[130:133], v[174:177], v[58:61]
	v_mfma_f32_16x16x32_bf16 v[54:57], v[138:141], v[174:177], v[54:57]
	v_mfma_f32_16x16x32_bf16 v[42:45], v[130:133], v[188:191], v[42:45]
	v_mfma_f32_16x16x32_bf16 v[38:41], v[138:141], v[188:191], v[38:41]
	v_mfma_f32_16x16x32_bf16 v[26:29], v[130:133], v[196:199], v[26:29]
	v_mfma_f32_16x16x32_bf16 v[22:25], v[138:141], v[196:199], v[22:25]
	v_mfma_f32_16x16x32_bf16 v[10:13], v[130:133], v[204:207], v[10:13]
	v_mfma_f32_16x16x32_bf16 v[6:9], v[138:141], v[204:207], v[6:9]
	v_mfma_f32_16x16x32_bf16 v[58:61], v[134:137], v[184:187], v[58:61]
	v_mfma_f32_16x16x32_bf16 v[54:57], v[142:145], v[184:187], v[54:57]
	v_mfma_f32_16x16x32_bf16 v[42:45], v[134:137], v[192:195], v[42:45]
	v_mfma_f32_16x16x32_bf16 v[38:41], v[142:145], v[192:195], v[38:41]
	v_mfma_f32_16x16x32_bf16 v[26:29], v[134:137], v[200:203], v[26:29]
	v_mfma_f32_16x16x32_bf16 v[22:25], v[142:145], v[200:203], v[22:25]
	v_mfma_f32_16x16x32_bf16 v[10:13], v[134:137], v[208:211], v[10:13]
	v_mfma_f32_16x16x32_bf16 v[6:9], v[142:145], v[208:211], v[6:9]
	s_setprio 0
	s_setprio 1
	v_mfma_f32_16x16x32_bf16 v[62:65], v[146:149], v[174:177], v[62:65]
	v_mfma_f32_16x16x32_bf16 v[50:53], v[166:169], v[174:177], v[50:53]
	v_mfma_f32_16x16x32_bf16 v[46:49], v[146:149], v[188:191], v[46:49]
	v_mfma_f32_16x16x32_bf16 v[34:37], v[166:169], v[188:191], v[34:37]
	v_mfma_f32_16x16x32_bf16 v[30:33], v[146:149], v[196:199], v[30:33]
	v_mfma_f32_16x16x32_bf16 v[18:21], v[166:169], v[196:199], v[18:21]
	v_mfma_f32_16x16x32_bf16 v[14:17], v[146:149], v[204:207], v[14:17]
	v_mfma_f32_16x16x32_bf16 v[2:5], v[166:169], v[204:207], v[2:5]
	v_mfma_f32_16x16x32_bf16 v[62:65], v[150:153], v[184:187], v[62:65]
	v_mfma_f32_16x16x32_bf16 v[50:53], v[170:173], v[184:187], v[50:53]
	v_mfma_f32_16x16x32_bf16 v[46:49], v[150:153], v[192:195], v[46:49]
	v_mfma_f32_16x16x32_bf16 v[34:37], v[170:173], v[192:195], v[34:37]
	v_mfma_f32_16x16x32_bf16 v[30:33], v[150:153], v[200:203], v[30:33]
	v_mfma_f32_16x16x32_bf16 v[18:21], v[170:173], v[200:203], v[18:21]
	v_mfma_f32_16x16x32_bf16 v[14:17], v[150:153], v[208:211], v[14:17]
	v_mfma_f32_16x16x32_bf16 v[2:5], v[170:173], v[208:211], v[2:5]
	s_setprio 0
	s_barrier
	s_add_i32 s69, 0, 0x18000
	s_add_i32 s70, 0, 0x1c000
	ds_read_b128 v[130:133], v181 offset:32768
	ds_read_b128 v[134:137], v181 offset:33792
	ds_read_b128 v[138:141], v181 offset:34816
	ds_read_b128 v[142:145], v181 offset:35840
	ds_read_b128 v[146:149], v181 offset:49152
	ds_read_b128 v[150:153], v181 offset:50176
	ds_read_b128 v[166:169], v181 offset:51200
	ds_read_b128 v[170:173], v181 offset:52224
	s_add_u32 s20, s20, s10
	s_addc_u32 s21, s21, s11
	s_mov_b32 m0, s57
	v_lshl_add_u64 v[224:225], s[20:21], 0, v[158:159]
	ds_read_b128 v[174:177], v183 offset:32768
	ds_read_b128 v[184:187], v183 offset:33792
	ds_read_b128 v[188:191], v183 offset:34816
	ds_read_b128 v[192:195], v183 offset:35840
	ds_read_b128 v[196:199], v183 offset:36864
	ds_read_b128 v[200:203], v183 offset:37888
	ds_read_b128 v[204:207], v183 offset:38912
	ds_read_b128 v[208:211], v183 offset:39936
	global_load_lds_dwordx4 v[224:225], off
	s_mov_b32 m0, s58
	v_lshl_add_u64 v[224:225], s[20:21], 0, v[156:157]
	global_load_lds_dwordx4 v[224:225], off
	s_waitcnt vmcnt(8)
	s_waitcnt lgkmcnt(0)
	s_barrier
	s_setprio 1
	s_waitcnt lgkmcnt(0)
	v_mfma_f32_16x16x32_bf16 v[122:125], v[130:133], v[174:177], v[122:125]
	v_mfma_f32_16x16x32_bf16 v[118:121], v[138:141], v[174:177], v[118:121]
	v_mfma_f32_16x16x32_bf16 v[106:109], v[130:133], v[188:191], v[106:109]
	v_mfma_f32_16x16x32_bf16 v[102:105], v[138:141], v[188:191], v[102:105]
	v_mfma_f32_16x16x32_bf16 v[90:93], v[130:133], v[196:199], v[90:93]
	v_mfma_f32_16x16x32_bf16 v[86:89], v[138:141], v[196:199], v[86:89]
	v_mfma_f32_16x16x32_bf16 v[74:77], v[130:133], v[204:207], v[74:77]
	v_mfma_f32_16x16x32_bf16 v[70:73], v[138:141], v[204:207], v[70:73]
	v_mfma_f32_16x16x32_bf16 v[122:125], v[134:137], v[184:187], v[122:125]
	v_mfma_f32_16x16x32_bf16 v[118:121], v[142:145], v[184:187], v[118:121]
	v_mfma_f32_16x16x32_bf16 v[106:109], v[134:137], v[192:195], v[106:109]
	v_mfma_f32_16x16x32_bf16 v[102:105], v[142:145], v[192:195], v[102:105]
	v_mfma_f32_16x16x32_bf16 v[90:93], v[134:137], v[200:203], v[90:93]
	v_mfma_f32_16x16x32_bf16 v[86:89], v[142:145], v[200:203], v[86:89]
	v_mfma_f32_16x16x32_bf16 v[74:77], v[134:137], v[208:211], v[74:77]
	v_mfma_f32_16x16x32_bf16 v[70:73], v[142:145], v[208:211], v[70:73]
	s_setprio 0
	s_setprio 1
	v_mfma_f32_16x16x32_bf16 v[126:129], v[146:149], v[174:177], v[126:129]
	v_mfma_f32_16x16x32_bf16 v[114:117], v[166:169], v[174:177], v[114:117]
	v_mfma_f32_16x16x32_bf16 v[110:113], v[146:149], v[188:191], v[110:113]
	v_mfma_f32_16x16x32_bf16 v[98:101], v[166:169], v[188:191], v[98:101]
	v_mfma_f32_16x16x32_bf16 v[94:97], v[146:149], v[196:199], v[94:97]
	v_mfma_f32_16x16x32_bf16 v[82:85], v[166:169], v[196:199], v[82:85]
	v_mfma_f32_16x16x32_bf16 v[78:81], v[146:149], v[204:207], v[78:81]
	v_mfma_f32_16x16x32_bf16 v[66:69], v[166:169], v[204:207], v[66:69]
	v_mfma_f32_16x16x32_bf16 v[126:129], v[150:153], v[184:187], v[126:129]
	v_mfma_f32_16x16x32_bf16 v[114:117], v[170:173], v[184:187], v[114:117]
	v_mfma_f32_16x16x32_bf16 v[110:113], v[150:153], v[192:195], v[110:113]
	v_mfma_f32_16x16x32_bf16 v[98:101], v[170:173], v[192:195], v[98:101]
	v_mfma_f32_16x16x32_bf16 v[94:97], v[150:153], v[200:203], v[94:97]
	v_mfma_f32_16x16x32_bf16 v[82:85], v[170:173], v[200:203], v[82:85]
	v_mfma_f32_16x16x32_bf16 v[78:81], v[150:153], v[208:211], v[78:81]
	v_mfma_f32_16x16x32_bf16 v[66:69], v[170:173], v[208:211], v[66:69]
	s_setprio 0
	s_barrier
; #define PG8_STAGE(bufoff, gbase, voff) do { _Pragma("unroll") for (int _i = 0; _i < 2; ++_i) \
;         __builtin_amdgcn_global_load_lds((const unsigned*)((const char*)(gbase) + (voff)[_i]), (PG8_LAS unsigned*)(lds + (bufoff) + ldsw + _i * 8192), 16, 0, 0); } while (0)
; #define PG8_LDA(dst, b, h) do { _Pragma("unroll") for (int m = 0; m < 4; ++m) _Pragma("unroll") for (int k = 0; k < 2; ++k) dst[m][k] = *(const PG8_LAS bf16x8*)(lds + PG8_SA(b, h) + aoff + m * 2048 + k * 1024); } while (0)
; #define PG8_MMA(ai, bj, At, Bt) do { __builtin_amdgcn_s_setprio(1); _Pragma("unroll") for (int m = 0; m < 4; ++m) _Pragma("unroll") for (int n = 0; n < 2; ++n) _Pragma("unroll") for (int k = 0; k < 2; ++k) \
;         acc[ai][bj][m][n] = __builtin_amdgcn_mfma_f32_16x16x32_bf16(Bt[n][k], At[m][k], acc[ai][bj][m][n], 0, 0, 0); __builtin_amdgcn_s_setprio(0); } while (0)
; #define PG8_WAIT_V(n) asm volatile("s_waitcnt vmcnt(" #n ")" ::: "memory")
; #define PG8_WAIT_L(n) asm volatile("s_waitcnt lgkmcnt(" #n ")" ::: "memory")
; #define PG8_BAR __builtin_amdgcn_s_barrier()
; #define PG8_SCHED __builtin_amdgcn_sched_barrier(0)
; template <class Epi, class Sched, bool ALIGN_EPI = false, bool SP2 = false>
; __device__ __forceinline__ void gemm_phase(PG8_LAS unsigned char* lds, const Gemm g, const Sched& S, const Epi& E) {
;     ...
;         for (int t = 0; t < nt; t += 2) {
;     ...
;             PG8_LDA(At, 1, 1); PG8_STAGE(PG8_SB(1, 0), b3, voffB); PG8_STAGE(PG8_SB(1, 1), b3 + hstep, voffB); PG8_STAGE(PG8_SA(1, 0), a3, voffA);
;             PG8_WAIT_V(8); PG8_WAIT_L(0); PG8_BAR; PG8_MMA(1, 0, At, B0); PG8_MMA(1, 1, At, B1); PG8_BAR; PG8_SCHED;
	s_add_i32 s20, s69, s23
	v_lshl_add_u64 v[178:179], v[178:179], 0, s[24:25]
	s_mov_b32 m0, s20
	ds_read_b128 v[174:177], v183 offset:49152
	ds_read_b128 v[184:187], v183 offset:50176
	ds_read_b128 v[188:191], v183 offset:51200
	ds_read_b128 v[192:195], v183 offset:52224
	ds_read_b128 v[196:199], v183 offset:53248
	ds_read_b128 v[200:203], v183 offset:54272
	ds_read_b128 v[204:207], v183 offset:55296
	ds_read_b128 v[208:211], v183 offset:56320
	global_load_lds_dwordx4 v[178:179], off
	v_lshl_add_u64 v[178:179], v[212:213], 0, s[24:25]
	s_add_i32 m0, s20, 0x2000
	s_add_i32 s20, s70, s23
	global_load_lds_dwordx4 v[178:179], off
	s_mov_b32 m0, s20
	v_lshl_add_u64 v[178:179], v[214:215], 0, s[24:25]
	global_load_lds_dwordx4 v[178:179], off
	s_add_i32 m0, s20, 0x2000
	v_lshl_add_u64 v[178:179], v[218:219], 0, s[24:25]
	global_load_lds_dwordx4 v[178:179], off
	s_mov_b32 m0, s59
	v_lshl_add_u64 v[178:179], v[220:221], 0, s[24:25]
	global_load_lds_dwordx4 v[178:179], off
	s_mov_b32 m0, s60
	v_lshl_add_u64 v[178:179], v[222:223], 0, s[24:25]
	global_load_lds_dwordx4 v[178:179], off
	s_waitcnt vmcnt(8)
	s_waitcnt lgkmcnt(0)
	s_barrier
	s_setprio 1
	s_waitcnt lgkmcnt(0)
	v_mfma_f32_16x16x32_bf16 v[58:61], v[130:133], v[174:177], v[58:61]
	v_mfma_f32_16x16x32_bf16 v[54:57], v[138:141], v[174:177], v[54:57]
	v_mfma_f32_16x16x32_bf16 v[42:45], v[130:133], v[188:191], v[42:45]
	v_mfma_f32_16x16x32_bf16 v[38:41], v[138:141], v[188:191], v[38:41]
	v_mfma_f32_16x16x32_bf16 v[26:29], v[130:133], v[196:199], v[26:29]
	v_mfma_f32_16x16x32_bf16 v[22:25], v[138:141], v[196:199], v[22:25]
	v_mfma_f32_16x16x32_bf16 v[10:13], v[130:133], v[204:207], v[10:13]
	v_mfma_f32_16x16x32_bf16 v[6:9], v[138:141], v[204:207], v[6:9]
	v_mfma_f32_16x16x32_bf16 v[58:61], v[134:137], v[184:187], v[58:61]
	v_mfma_f32_16x16x32_bf16 v[54:57], v[142:145], v[184:187], v[54:57]
	v_mfma_f32_16x16x32_bf16 v[42:45], v[134:137], v[192:195], v[42:45]
	v_mfma_f32_16x16x32_bf16 v[38:41], v[142:145], v[192:195], v[38:41]
	v_mfma_f32_16x16x32_bf16 v[26:29], v[134:137], v[200:203], v[26:29]
	v_mfma_f32_16x16x32_bf16 v[22:25], v[142:145], v[200:203], v[22:25]
	v_mfma_f32_16x16x32_bf16 v[10:13], v[134:137], v[208:211], v[10:13]
	v_mfma_f32_16x16x32_bf16 v[6:9], v[142:145], v[208:211], v[6:9]
	s_setprio 0
	s_setprio 1
	v_mfma_f32_16x16x32_bf16 v[62:65], v[146:149], v[174:177], v[62:65]
	v_mfma_f32_16x16x32_bf16 v[50:53], v[166:169], v[174:177], v[50:53]
	v_mfma_f32_16x16x32_bf16 v[46:49], v[146:149], v[188:191], v[46:49]
	v_mfma_f32_16x16x32_bf16 v[34:37], v[166:169], v[188:191], v[34:37]
	v_mfma_f32_16x16x32_bf16 v[30:33], v[146:149], v[196:199], v[30:33]
	v_mfma_f32_16x16x32_bf16 v[18:21], v[166:169], v[196:199], v[18:21]
	v_mfma_f32_16x16x32_bf16 v[14:17], v[146:149], v[204:207], v[14:17]
	v_mfma_f32_16x16x32_bf16 v[2:5], v[166:169], v[204:207], v[2:5]
	v_mfma_f32_16x16x32_bf16 v[62:65], v[150:153], v[184:187], v[62:65]
	v_mfma_f32_16x16x32_bf16 v[50:53], v[170:173], v[184:187], v[50:53]
	v_mfma_f32_16x16x32_bf16 v[46:49], v[150:153], v[192:195], v[46:49]
	v_mfma_f32_16x16x32_bf16 v[34:37], v[170:173], v[192:195], v[34:37]
	v_mfma_f32_16x16x32_bf16 v[30:33], v[150:153], v[200:203], v[30:33]
	v_mfma_f32_16x16x32_bf16 v[18:21], v[170:173], v[200:203], v[18:21]
	v_mfma_f32_16x16x32_bf16 v[14:17], v[150:153], v[208:211], v[14:17]
	v_mfma_f32_16x16x32_bf16 v[2:5], v[170:173], v[208:211], v[2:5]
	s_setprio 0
	s_barrier
	s_add_u32 s8, s8, 0x100
	s_addc_u32 s9, s9, 0
	s_add_u32 s52, s52, 0x100
	s_addc_u32 s53, s53, 0
	s_cmp_ge_i32 s68, s62
	s_mov_b32 s20, s68
	s_cbranch_scc0 .LBB0_641
